# SSM: first-half partial-y exchange moved from scattered 64-B row pieces in d_out to dense per-(pair,dir) 32 KiB buffers in the dead H region (1 KiB contiguous per store/load)
# speedup vs baseline: 1.0050x; 1.0050x over previous
.LBB0_340:
	s_cmp_lt_i32 s96, 4
	s_cselect_b64 s[0:1], -1, 0
	s_and_b64 s[8:9], s[0:1], s[4:5]
	s_andn2_b64 vcc, exec, s[8:9]
	s_cbranch_vccnz .LBB0_393
	v_cmp_gt_u32_e32 vcc, 2, v190
	s_and_saveexec_b64 s[0:1], vcc
	v_lshlrev_b32_e32 v2, 2, v190
	v_add_u32_e32 v2, 0x21000, v2
	v_mov_b32_e32 v3, 0
	ds_write_b32 v2, v3
	s_mov_b64 exec, s[0:1]
	v_and_b32_e32 v172, 31, v191
	v_lshrrev_b32_e32 v173, 5, v191
	v_and_b32_e32 v174, 1, v191
	v_and_b32_e32 v175, 15, v191
	v_lshrrev_b32_e32 v176, 4, v191
	s_mul_i32 s20, s89, 0x3200
	v_lshl_add_u32 v151, v191, 2, s20
	v_mul_u32_u24_e32 v182, 0x110, v175
	v_lshl_add_u32 v182, v176, 4, v182
	v_add_u32_e32 v152, s20, v182
	v_mul_u32_u24_e32 v182, 0x1800, v172
	v_lshl_add_u32 v150, v173, 4, v182
	v_lshlrev_b32_e32 v182, 5, v172
	v_lshl_add_u32 v182, v173, 4, v182
	s_add_u32 s22, s20, 0x2200
	v_add_u32_e32 v162, s22, v182
	v_lshlrev_b32_e32 v182, 5, v175
	v_lshl_add_u32 v182, v176, 3, v182
	v_add_u32_e32 v163, s22, v182
	v_mul_u32_u24_e32 v182, 0x1800, v175
	v_lshl_add_u32 v154, v176, 3, v182
	v_add_u32_e32 v158, 0x18000, v154
	v_lshlrev_b32_e32 v182, 12, v175
	v_lshlrev_b32_e32 v182, 6, v175
	v_lshl_add_u32 v153, v176, 4, v182
	v_add_u32_e32 v157, 0x400, v153
	v_lshlrev_b32_e32 v182, 11, v175
	v_lshl_add_u32 v156, v176, 3, v182
	v_add_u32_e32 v159, 0x8000, v156
	s_and_b32 s21, s89, 3
	s_lshl_b32 s21, s21, 13
	s_add_u32 s21, s21, 0x19000
	v_lshlrev_b32_e32 v182, 5, v175
	v_lshl_add_u32 v182, v176, 3, v182
	v_add_u32_e32 v155, s21, v182
	v_lshrrev_b32_e32 v182, 4, v172
	v_lshlrev_b32_e32 v182, 10, v182
	v_lshl_add_u32 v182, v175, 4, v182
	v_lshl_add_u32 v177, v173, 8, v182
	v_lshrrev_b32_e32 v182, 1, v176
	v_lshlrev_b32_e32 v182, 8, v182
	v_and_b32_e32 v183, 1, v176
	v_lshl_add_u32 v182, v183, 3, v182
	v_lshl_add_u32 v178, v175, 4, v182
	v_lshrrev_b32_e32 v182, 1, v172
	v_lshl_add_u32 v182, v173, 5, v182
	v_lshlrev_b32_e32 v179, 3, v182
	v_lshlrev_b32_e32 v183, 14, v174
	v_lshl_add_u32 v180, v182, 2, v183
	v_lshlrev_b32_e32 v181, 4, v176
	s_waitcnt vmcnt(0) lgkmcnt(0)
	s_barrier
	s_cmp_lt_u32 s89, 4
	s_cbranch_scc0 .Lssm_ctx
	s_lshr_b32 s21, s89, 1
	s_and_b32 s22, s2, 7
	s_lshl_b32 s22, s22, 6
	s_lshr_b32 s26, s2, 3
	s_lshl_b32 s26, s26, 1
	s_add_u32 s22, s22, s26
	s_add_u32 s22, s22, s21
	s_lshr_b32 s23, s22, 6
	s_and_b32 s24, s22, 63
	s_lshl_b32 s25, s23, 10
	s_add_u32 s25, s25, 0x2000
	s_and_b32 s26, s89, 1
	s_cmp_eq_u32 s26, 0
	s_cbranch_scc0 .Lssm_lat_bwd
	s_add_u32 s28, s24, 0
	s_lshl_b32 s29, s28, 13
	s_add_u32 s29, s29, 0x200000
	s_add_u32 s10, s62, s29
	s_addc_u32 s11, s63, 0
	global_load_dwordx4 v[84:87], v177, s[10:11]
	global_load_dwordx4 v[88:91], v177, s[10:11] offset:2048
	s_add_u32 s12, s10, 0x1000
	s_addc_u32 s13, s11, 0
	global_load_dwordx4 v[92:95], v177, s[12:13]
	global_load_dwordx4 v[96:99], v177, s[12:13] offset:2048
	s_lshl_b32 s29, s28, 12
	s_add_u32 s29, s29, 0x300000
	s_add_u32 s16, s62, s29
	s_addc_u32 s17, s63, 0
	global_load_dwordx2 v[2:3], v178, s[16:17]
	global_load_dwordx2 v[4:5], v178, s[16:17] offset:1024
	global_load_dwordx2 v[6:7], v178, s[16:17] offset:512
	global_load_dwordx2 v[8:9], v178, s[16:17] offset:1536
	global_load_dwordx2 v[10:11], v178, s[16:17] offset:2048
	global_load_dwordx2 v[12:13], v178, s[16:17] offset:3072
	global_load_dwordx2 v[14:15], v178, s[16:17] offset:2560
	global_load_dwordx2 v[16:17], v178, s[16:17] offset:3584
	s_lshl_b32 s29, s28, 9
	s_add_u32 s29, s29, 0x100000
	s_add_u32 s18, s62, s29
	s_addc_u32 s19, s63, 0
	global_load_dwordx2 v[116:117], v179, s[18:19]
	global_load_dwordx2 v[118:119], v179, s[18:19] offset:128
	s_lshl_b32 s30, s23, 1
	s_lshl_b32 s30, s30, 15
	s_lshl_b32 s31, s24, 8
	s_add_u32 s30, s30, s31
	v_readlane_b32 s34, v254, 10
	v_readlane_b32 s35, v254, 11
	s_nop 3
	s_add_u32 s34, s34, s30
	s_addc_u32 s35, s35, 0
	global_load_dword v120, v180, s[34:35]
	global_load_dword v121, v180, s[34:35] offset:64
	v_readlane_b32 s34, v254, 28
	v_readlane_b32 s35, v254, 29
	s_nop 3
	s_lshl_b32 s31, s24, 6
	s_add_u32 s34, s34, s31
	s_addc_u32 s35, s35, 0
	global_load_dwordx4 v[164:167], v181, s[34:35]
	s_mul_i32 s31, s25, 0x1800
	s_lshl_b32 s29, s24, 5
	s_add_u32 s31, s31, s29
	s_add_u32 s31, s31, 0x8801000
	s_add_u32 s4, s62, s31
	s_addc_u32 s5, s63, 0
	s_lshl_b32 s31, s22, 1
	s_lshl_b32 s31, s31, 15
	s_add_u32 s31, s31, 0x4800000
	s_add_u32 s6, s62, s31
	s_addc_u32 s7, s63, 0
	s_add_u32 s34, s4, 0
	s_addc_u32 s35, s5, 0
	global_load_dwordx4 v[80:83], v150, s[34:35]
	s_mov_b64 s[10:11], s[34:35]
	s_add_u32 s10, s10, 196608
	s_addc_u32 s11, s11, 0
	global_load_dwordx4 v[144:147], v150, s[10:11]
	s_mov_b64 s[34:35], s[10:11]
	s_add_u32 s10, s10, 196608
	s_addc_u32 s11, s11, 0
	s_add_u32 s12, s6, 0
	s_addc_u32 s13, s7, 0
	s_mov_b32 s14, 0
	s_mov_b32 s40, 0xffff0000
	s_waitcnt vmcnt(0)
	v_and_b32_e32 v182, 0xffff, v2
	v_lshrrev_b32_e32 v183, 16, v2
	v_and_b32_e32 v184, 0xffff, v3
	v_lshrrev_b32_e32 v185, 16, v3
	v_lshl_or_b32 v100, v4, 16, v182
	v_and_or_b32 v101, v4, s40, v183
	v_lshl_or_b32 v102, v5, 16, v184
	v_and_or_b32 v103, v5, s40, v185
	v_and_b32_e32 v182, 0xffff, v6
	v_lshrrev_b32_e32 v183, 16, v6
	v_and_b32_e32 v184, 0xffff, v7
	v_lshrrev_b32_e32 v185, 16, v7
	v_lshl_or_b32 v104, v8, 16, v182
	v_and_or_b32 v105, v8, s40, v183
	v_lshl_or_b32 v106, v9, 16, v184
	v_and_or_b32 v107, v9, s40, v185
	v_and_b32_e32 v182, 0xffff, v10
	v_lshrrev_b32_e32 v183, 16, v10
	v_and_b32_e32 v184, 0xffff, v11
	v_lshrrev_b32_e32 v185, 16, v11
	v_lshl_or_b32 v108, v12, 16, v182
	v_and_or_b32 v109, v12, s40, v183
	v_lshl_or_b32 v110, v13, 16, v184
	v_and_or_b32 v111, v13, s40, v185
	v_and_b32_e32 v182, 0xffff, v14
	v_lshrrev_b32_e32 v183, 16, v14
	v_and_b32_e32 v184, 0xffff, v15
	v_lshrrev_b32_e32 v185, 16, v15
	v_lshl_or_b32 v112, v16, 16, v182
	v_and_or_b32 v113, v16, s40, v183
	v_lshl_or_b32 v114, v17, 16, v184
	v_and_or_b32 v115, v17, s40, v185
	v_cmp_eq_u32_e32 vcc, 1, v174
	v_xor_b32_e32 v182, 0x80000000, v117
	v_xor_b32_e32 v183, 0x80000000, v119
	s_nop 1
	v_cndmask_b32_e32 v122, v182, v117, vcc
	v_cndmask_b32_e32 v123, v183, v119, vcc
.Lssm_tileA_d0m0:
	s_waitcnt vmcnt(5)
	v_mfma_f32_32x32x16_bf16 v[16:31], v[80:83], v[84:87], 0
	v_mfma_f32_32x32x16_bf16 v[32:47], v[80:83], v[88:91], 0
	v_mfma_f32_32x32x16_bf16 v[48:63], v[80:83], v[92:95], 0
	v_mfma_f32_32x32x16_bf16 v[64:79], v[80:83], v[96:99], 0
	s_nop 11
	global_load_dwordx4 v[80:83], v150, s[10:11]
	s_add_u32 s34, s34, 196608
	s_addc_u32 s35, s35, 0
	s_add_u32 s10, s10, 196608
	s_addc_u32 s11, s11, 0
	v_permlane32_swap_b32_e32 v16, v48
	v_permlane32_swap_b32_e32 v17, v49
	v_permlane32_swap_b32_e32 v18, v50
	v_permlane32_swap_b32_e32 v19, v51
	v_permlane32_swap_b32_e32 v20, v52
	v_permlane32_swap_b32_e32 v21, v53
	v_permlane32_swap_b32_e32 v22, v54
	v_permlane32_swap_b32_e32 v23, v55
	v_permlane32_swap_b32_e32 v24, v56
	v_permlane32_swap_b32_e32 v25, v57
	v_permlane32_swap_b32_e32 v26, v58
	v_permlane32_swap_b32_e32 v27, v59
	v_permlane32_swap_b32_e32 v28, v60
	v_permlane32_swap_b32_e32 v29, v61
	v_permlane32_swap_b32_e32 v30, v62
	v_permlane32_swap_b32_e32 v31, v63
	v_permlane32_swap_b32_e32 v32, v64
	v_permlane32_swap_b32_e32 v33, v65
	v_permlane32_swap_b32_e32 v34, v66
	v_permlane32_swap_b32_e32 v35, v67
	v_permlane32_swap_b32_e32 v36, v68
	v_permlane32_swap_b32_e32 v37, v69
	v_permlane32_swap_b32_e32 v38, v70
	v_permlane32_swap_b32_e32 v39, v71
	v_permlane32_swap_b32_e32 v40, v72
	v_permlane32_swap_b32_e32 v41, v73
	v_permlane32_swap_b32_e32 v42, v74
	v_permlane32_swap_b32_e32 v43, v75
	v_permlane32_swap_b32_e32 v44, v76
	v_permlane32_swap_b32_e32 v45, v77
	v_permlane32_swap_b32_e32 v46, v78
	v_permlane32_swap_b32_e32 v47, v79
	v_fmac_f32_e32 v16, v116, v120
	v_fmac_f32_e32 v32, v118, v121
	v_fmac_f32_dpp v16, v120, v122 quad_perm:[1,0,3,2] row_mask:0xf bank_mask:0xf
	v_fmac_f32_dpp v32, v121, v123 quad_perm:[1,0,3,2] row_mask:0xf bank_mask:0xf
	v_cvt_pk_bf16_f32 v148, v16, v32
	ds_write_b32 v151, v148
	v_fmac_f32_e32 v17, v116, v16
	v_fmac_f32_e32 v33, v118, v32
	v_fmac_f32_dpp v17, v16, v122 quad_perm:[1,0,3,2] row_mask:0xf bank_mask:0xf
	v_fmac_f32_dpp v33, v32, v123 quad_perm:[1,0,3,2] row_mask:0xf bank_mask:0xf
	v_cvt_pk_bf16_f32 v149, v17, v33
	ds_write_b32 v151, v149 offset:272
	v_fmac_f32_e32 v18, v116, v17
	v_fmac_f32_e32 v34, v118, v33
	v_fmac_f32_dpp v18, v17, v122 quad_perm:[1,0,3,2] row_mask:0xf bank_mask:0xf
	v_fmac_f32_dpp v34, v33, v123 quad_perm:[1,0,3,2] row_mask:0xf bank_mask:0xf
	v_cvt_pk_bf16_f32 v148, v18, v34
	ds_write_b32 v151, v148 offset:544
	v_fmac_f32_e32 v19, v116, v18
	v_fmac_f32_e32 v35, v118, v34
	v_fmac_f32_dpp v19, v18, v122 quad_perm:[1,0,3,2] row_mask:0xf bank_mask:0xf
	v_fmac_f32_dpp v35, v34, v123 quad_perm:[1,0,3,2] row_mask:0xf bank_mask:0xf
	v_cvt_pk_bf16_f32 v149, v19, v35
	ds_write_b32 v151, v149 offset:816
	v_fmac_f32_e32 v48, v116, v19
	v_fmac_f32_e32 v64, v118, v35
	v_fmac_f32_dpp v48, v19, v122 quad_perm:[1,0,3,2] row_mask:0xf bank_mask:0xf
	v_fmac_f32_dpp v64, v35, v123 quad_perm:[1,0,3,2] row_mask:0xf bank_mask:0xf
	v_cvt_pk_bf16_f32 v148, v48, v64
	ds_write_b32 v151, v148 offset:1088
	v_fmac_f32_e32 v49, v116, v48
	v_fmac_f32_e32 v65, v118, v64
	v_fmac_f32_dpp v49, v48, v122 quad_perm:[1,0,3,2] row_mask:0xf bank_mask:0xf
	v_fmac_f32_dpp v65, v64, v123 quad_perm:[1,0,3,2] row_mask:0xf bank_mask:0xf
	v_cvt_pk_bf16_f32 v149, v49, v65
	ds_write_b32 v151, v149 offset:1360
	v_fmac_f32_e32 v50, v116, v49
	v_fmac_f32_e32 v66, v118, v65
	v_fmac_f32_dpp v50, v49, v122 quad_perm:[1,0,3,2] row_mask:0xf bank_mask:0xf
	v_fmac_f32_dpp v66, v65, v123 quad_perm:[1,0,3,2] row_mask:0xf bank_mask:0xf
	v_cvt_pk_bf16_f32 v148, v50, v66
	ds_write_b32 v151, v148 offset:1632
	v_fmac_f32_e32 v51, v116, v50
	v_fmac_f32_e32 v67, v118, v66
	v_fmac_f32_dpp v51, v50, v122 quad_perm:[1,0,3,2] row_mask:0xf bank_mask:0xf
	v_fmac_f32_dpp v67, v66, v123 quad_perm:[1,0,3,2] row_mask:0xf bank_mask:0xf
	v_cvt_pk_bf16_f32 v149, v51, v67
	ds_write_b32 v151, v149 offset:1904
	v_fmac_f32_e32 v20, v116, v51
	v_fmac_f32_e32 v36, v118, v67
	v_fmac_f32_dpp v20, v51, v122 quad_perm:[1,0,3,2] row_mask:0xf bank_mask:0xf
	v_fmac_f32_dpp v36, v67, v123 quad_perm:[1,0,3,2] row_mask:0xf bank_mask:0xf
	v_cvt_pk_bf16_f32 v148, v20, v36
	ds_write_b32 v151, v148 offset:2176
	v_fmac_f32_e32 v21, v116, v20
	v_fmac_f32_e32 v37, v118, v36
	v_fmac_f32_dpp v21, v20, v122 quad_perm:[1,0,3,2] row_mask:0xf bank_mask:0xf
	v_fmac_f32_dpp v37, v36, v123 quad_perm:[1,0,3,2] row_mask:0xf bank_mask:0xf
	v_cvt_pk_bf16_f32 v149, v21, v37
	ds_write_b32 v151, v149 offset:2448
	v_fmac_f32_e32 v22, v116, v21
	v_fmac_f32_e32 v38, v118, v37
	v_fmac_f32_dpp v22, v21, v122 quad_perm:[1,0,3,2] row_mask:0xf bank_mask:0xf
	v_fmac_f32_dpp v38, v37, v123 quad_perm:[1,0,3,2] row_mask:0xf bank_mask:0xf
	v_cvt_pk_bf16_f32 v148, v22, v38
	ds_write_b32 v151, v148 offset:2720
	v_fmac_f32_e32 v23, v116, v22
	v_fmac_f32_e32 v39, v118, v38
	v_fmac_f32_dpp v23, v22, v122 quad_perm:[1,0,3,2] row_mask:0xf bank_mask:0xf
	v_fmac_f32_dpp v39, v38, v123 quad_perm:[1,0,3,2] row_mask:0xf bank_mask:0xf
	v_cvt_pk_bf16_f32 v149, v23, v39
	ds_write_b32 v151, v149 offset:2992
	v_fmac_f32_e32 v52, v116, v23
	v_fmac_f32_e32 v68, v118, v39
	v_fmac_f32_dpp v52, v23, v122 quad_perm:[1,0,3,2] row_mask:0xf bank_mask:0xf
	v_fmac_f32_dpp v68, v39, v123 quad_perm:[1,0,3,2] row_mask:0xf bank_mask:0xf
	v_cvt_pk_bf16_f32 v148, v52, v68
	ds_write_b32 v151, v148 offset:3264
	v_fmac_f32_e32 v53, v116, v52
	v_fmac_f32_e32 v69, v118, v68
	v_fmac_f32_dpp v53, v52, v122 quad_perm:[1,0,3,2] row_mask:0xf bank_mask:0xf
	v_fmac_f32_dpp v69, v68, v123 quad_perm:[1,0,3,2] row_mask:0xf bank_mask:0xf
	v_cvt_pk_bf16_f32 v149, v53, v69
	ds_write_b32 v151, v149 offset:3536
	v_fmac_f32_e32 v54, v116, v53
	v_fmac_f32_e32 v70, v118, v69
	v_fmac_f32_dpp v54, v53, v122 quad_perm:[1,0,3,2] row_mask:0xf bank_mask:0xf
	v_fmac_f32_dpp v70, v69, v123 quad_perm:[1,0,3,2] row_mask:0xf bank_mask:0xf
	v_cvt_pk_bf16_f32 v148, v54, v70
	ds_write_b32 v151, v148 offset:3808
	v_fmac_f32_e32 v55, v116, v54
	v_fmac_f32_e32 v71, v118, v70
	v_fmac_f32_dpp v55, v54, v122 quad_perm:[1,0,3,2] row_mask:0xf bank_mask:0xf
	v_fmac_f32_dpp v71, v70, v123 quad_perm:[1,0,3,2] row_mask:0xf bank_mask:0xf
	v_cvt_pk_bf16_f32 v149, v55, v71
	ds_write_b32 v151, v149 offset:4080
	v_fmac_f32_e32 v24, v116, v55
	v_fmac_f32_e32 v40, v118, v71
	v_fmac_f32_dpp v24, v55, v122 quad_perm:[1,0,3,2] row_mask:0xf bank_mask:0xf
	v_fmac_f32_dpp v40, v71, v123 quad_perm:[1,0,3,2] row_mask:0xf bank_mask:0xf
	v_cvt_pk_bf16_f32 v148, v24, v40
	ds_write_b32 v151, v148 offset:4352
	v_fmac_f32_e32 v25, v116, v24
	v_fmac_f32_e32 v41, v118, v40
	v_fmac_f32_dpp v25, v24, v122 quad_perm:[1,0,3,2] row_mask:0xf bank_mask:0xf
	v_fmac_f32_dpp v41, v40, v123 quad_perm:[1,0,3,2] row_mask:0xf bank_mask:0xf
	v_cvt_pk_bf16_f32 v149, v25, v41
	ds_write_b32 v151, v149 offset:4624
	v_fmac_f32_e32 v26, v116, v25
	v_fmac_f32_e32 v42, v118, v41
	v_fmac_f32_dpp v26, v25, v122 quad_perm:[1,0,3,2] row_mask:0xf bank_mask:0xf
	v_fmac_f32_dpp v42, v41, v123 quad_perm:[1,0,3,2] row_mask:0xf bank_mask:0xf
	v_cvt_pk_bf16_f32 v148, v26, v42
	ds_write_b32 v151, v148 offset:4896
	v_fmac_f32_e32 v27, v116, v26
	v_fmac_f32_e32 v43, v118, v42
	v_fmac_f32_dpp v27, v26, v122 quad_perm:[1,0,3,2] row_mask:0xf bank_mask:0xf
	v_fmac_f32_dpp v43, v42, v123 quad_perm:[1,0,3,2] row_mask:0xf bank_mask:0xf
	v_cvt_pk_bf16_f32 v149, v27, v43
	ds_write_b32 v151, v149 offset:5168
	v_fmac_f32_e32 v56, v116, v27
	v_fmac_f32_e32 v72, v118, v43
	v_fmac_f32_dpp v56, v27, v122 quad_perm:[1,0,3,2] row_mask:0xf bank_mask:0xf
	v_fmac_f32_dpp v72, v43, v123 quad_perm:[1,0,3,2] row_mask:0xf bank_mask:0xf
	v_cvt_pk_bf16_f32 v148, v56, v72
	ds_write_b32 v151, v148 offset:5440
	v_fmac_f32_e32 v57, v116, v56
	v_fmac_f32_e32 v73, v118, v72
	v_fmac_f32_dpp v57, v56, v122 quad_perm:[1,0,3,2] row_mask:0xf bank_mask:0xf
	v_fmac_f32_dpp v73, v72, v123 quad_perm:[1,0,3,2] row_mask:0xf bank_mask:0xf
	v_cvt_pk_bf16_f32 v149, v57, v73
	ds_write_b32 v151, v149 offset:5712
	v_fmac_f32_e32 v58, v116, v57
	v_fmac_f32_e32 v74, v118, v73
	v_fmac_f32_dpp v58, v57, v122 quad_perm:[1,0,3,2] row_mask:0xf bank_mask:0xf
	v_fmac_f32_dpp v74, v73, v123 quad_perm:[1,0,3,2] row_mask:0xf bank_mask:0xf
	v_cvt_pk_bf16_f32 v148, v58, v74
	ds_write_b32 v151, v148 offset:5984
	v_fmac_f32_e32 v59, v116, v58
	v_fmac_f32_e32 v75, v118, v74
	v_fmac_f32_dpp v59, v58, v122 quad_perm:[1,0,3,2] row_mask:0xf bank_mask:0xf
	v_fmac_f32_dpp v75, v74, v123 quad_perm:[1,0,3,2] row_mask:0xf bank_mask:0xf
	v_cvt_pk_bf16_f32 v149, v59, v75
	ds_write_b32 v151, v149 offset:6256
	v_fmac_f32_e32 v28, v116, v59
	v_fmac_f32_e32 v44, v118, v75
	v_fmac_f32_dpp v28, v59, v122 quad_perm:[1,0,3,2] row_mask:0xf bank_mask:0xf
	v_fmac_f32_dpp v44, v75, v123 quad_perm:[1,0,3,2] row_mask:0xf bank_mask:0xf
	v_cvt_pk_bf16_f32 v148, v28, v44
	ds_write_b32 v151, v148 offset:6528
	v_fmac_f32_e32 v29, v116, v28
	v_fmac_f32_e32 v45, v118, v44
	v_fmac_f32_dpp v29, v28, v122 quad_perm:[1,0,3,2] row_mask:0xf bank_mask:0xf
	v_fmac_f32_dpp v45, v44, v123 quad_perm:[1,0,3,2] row_mask:0xf bank_mask:0xf
	v_cvt_pk_bf16_f32 v149, v29, v45
	ds_write_b32 v151, v149 offset:6800
	v_fmac_f32_e32 v30, v116, v29
	v_fmac_f32_e32 v46, v118, v45
	v_fmac_f32_dpp v30, v29, v122 quad_perm:[1,0,3,2] row_mask:0xf bank_mask:0xf
	v_fmac_f32_dpp v46, v45, v123 quad_perm:[1,0,3,2] row_mask:0xf bank_mask:0xf
	v_cvt_pk_bf16_f32 v148, v30, v46
	ds_write_b32 v151, v148 offset:7072
	v_fmac_f32_e32 v31, v116, v30
	v_fmac_f32_e32 v47, v118, v46
	v_fmac_f32_dpp v31, v30, v122 quad_perm:[1,0,3,2] row_mask:0xf bank_mask:0xf
	v_fmac_f32_dpp v47, v46, v123 quad_perm:[1,0,3,2] row_mask:0xf bank_mask:0xf
	v_cvt_pk_bf16_f32 v149, v31, v47
	ds_write_b32 v151, v149 offset:7344
	v_fmac_f32_e32 v60, v116, v31
	v_fmac_f32_e32 v76, v118, v47
	v_fmac_f32_dpp v60, v31, v122 quad_perm:[1,0,3,2] row_mask:0xf bank_mask:0xf
	v_fmac_f32_dpp v76, v47, v123 quad_perm:[1,0,3,2] row_mask:0xf bank_mask:0xf
	v_cvt_pk_bf16_f32 v148, v60, v76
	ds_write_b32 v151, v148 offset:7616
	v_fmac_f32_e32 v61, v116, v60
	v_fmac_f32_e32 v77, v118, v76
	v_fmac_f32_dpp v61, v60, v122 quad_perm:[1,0,3,2] row_mask:0xf bank_mask:0xf
	v_fmac_f32_dpp v77, v76, v123 quad_perm:[1,0,3,2] row_mask:0xf bank_mask:0xf
	v_cvt_pk_bf16_f32 v149, v61, v77
	ds_write_b32 v151, v149 offset:7888
	v_fmac_f32_e32 v62, v116, v61
	v_fmac_f32_e32 v78, v118, v77
	v_fmac_f32_dpp v62, v61, v122 quad_perm:[1,0,3,2] row_mask:0xf bank_mask:0xf
	v_fmac_f32_dpp v78, v77, v123 quad_perm:[1,0,3,2] row_mask:0xf bank_mask:0xf
	v_cvt_pk_bf16_f32 v148, v62, v78
	ds_write_b32 v151, v148 offset:8160
	v_fmac_f32_e32 v63, v116, v62
	v_fmac_f32_e32 v79, v118, v78
	v_fmac_f32_dpp v63, v62, v122 quad_perm:[1,0,3,2] row_mask:0xf bank_mask:0xf
	v_fmac_f32_dpp v79, v78, v123 quad_perm:[1,0,3,2] row_mask:0xf bank_mask:0xf
	v_cvt_pk_bf16_f32 v149, v63, v79
	ds_write_b32 v151, v149 offset:8432
	v_mov_b32_e32 v120, v63
	v_mov_b32_e32 v121, v79
	ds_read_b128 v[124:127], v152
	ds_read_b128 v[128:131], v152 offset:64
	ds_read_b128 v[132:135], v152 offset:128
	ds_read_b128 v[136:139], v152 offset:192
	s_waitcnt lgkmcnt(3)
	v_mfma_f32_16x16x32_bf16 v[140:143], v[100:103], v[124:127], 0
	s_waitcnt lgkmcnt(2)
	v_mfma_f32_16x16x32_bf16 v[140:143], v[104:107], v[128:131], v[140:143]
	s_waitcnt lgkmcnt(1)
	v_mfma_f32_16x16x32_bf16 v[140:143], v[108:111], v[132:135], v[140:143]
	s_waitcnt lgkmcnt(0)
	v_mfma_f32_16x16x32_bf16 v[140:143], v[112:115], v[136:139], v[140:143]
	s_nop 9
	global_store_dwordx4 v153, v[140:143], s[12:13]
	s_nop 1
	ds_read_b128 v[124:127], v152 offset:4352
	ds_read_b128 v[128:131], v152 offset:4416
	ds_read_b128 v[132:135], v152 offset:4480
	ds_read_b128 v[136:139], v152 offset:4544
	s_waitcnt lgkmcnt(3)
	v_mfma_f32_16x16x32_bf16 v[140:143], v[100:103], v[124:127], 0
	s_waitcnt lgkmcnt(2)
	v_mfma_f32_16x16x32_bf16 v[140:143], v[104:107], v[128:131], v[140:143]
	s_waitcnt lgkmcnt(1)
	v_mfma_f32_16x16x32_bf16 v[140:143], v[108:111], v[132:135], v[140:143]
	s_waitcnt lgkmcnt(0)
	v_mfma_f32_16x16x32_bf16 v[140:143], v[112:115], v[136:139], v[140:143]
	s_nop 9
	global_store_dwordx4 v157, v[140:143], s[12:13]
	s_nop 1
	s_add_u32 s12, s12, 2048
	s_addc_u32 s13, s13, 0
	s_waitcnt vmcnt(5)
	v_mfma_f32_32x32x16_bf16 v[16:31], v[144:147], v[84:87], 0
	v_mfma_f32_32x32x16_bf16 v[32:47], v[144:147], v[88:91], 0
	v_mfma_f32_32x32x16_bf16 v[48:63], v[144:147], v[92:95], 0
	v_mfma_f32_32x32x16_bf16 v[64:79], v[144:147], v[96:99], 0
	s_nop 11
	global_load_dwordx4 v[144:147], v150, s[10:11]
	s_add_u32 s34, s34, 196608
	s_addc_u32 s35, s35, 0
	s_add_u32 s10, s10, 196608
	s_addc_u32 s11, s11, 0
	v_permlane32_swap_b32_e32 v16, v48
	v_permlane32_swap_b32_e32 v17, v49
	v_permlane32_swap_b32_e32 v18, v50
	v_permlane32_swap_b32_e32 v19, v51
	v_permlane32_swap_b32_e32 v20, v52
	v_permlane32_swap_b32_e32 v21, v53
	v_permlane32_swap_b32_e32 v22, v54
	v_permlane32_swap_b32_e32 v23, v55
	v_permlane32_swap_b32_e32 v24, v56
	v_permlane32_swap_b32_e32 v25, v57
	v_permlane32_swap_b32_e32 v26, v58
	v_permlane32_swap_b32_e32 v27, v59
	v_permlane32_swap_b32_e32 v28, v60
	v_permlane32_swap_b32_e32 v29, v61
	v_permlane32_swap_b32_e32 v30, v62
	v_permlane32_swap_b32_e32 v31, v63
	v_permlane32_swap_b32_e32 v32, v64
	v_permlane32_swap_b32_e32 v33, v65
	v_permlane32_swap_b32_e32 v34, v66
	v_permlane32_swap_b32_e32 v35, v67
	v_permlane32_swap_b32_e32 v36, v68
	v_permlane32_swap_b32_e32 v37, v69
	v_permlane32_swap_b32_e32 v38, v70
	v_permlane32_swap_b32_e32 v39, v71
	v_permlane32_swap_b32_e32 v40, v72
	v_permlane32_swap_b32_e32 v41, v73
	v_permlane32_swap_b32_e32 v42, v74
	v_permlane32_swap_b32_e32 v43, v75
	v_permlane32_swap_b32_e32 v44, v76
	v_permlane32_swap_b32_e32 v45, v77
	v_permlane32_swap_b32_e32 v46, v78
	v_permlane32_swap_b32_e32 v47, v79
	v_fmac_f32_e32 v16, v116, v120
	v_fmac_f32_e32 v32, v118, v121
	v_fmac_f32_dpp v16, v120, v122 quad_perm:[1,0,3,2] row_mask:0xf bank_mask:0xf
	v_fmac_f32_dpp v32, v121, v123 quad_perm:[1,0,3,2] row_mask:0xf bank_mask:0xf
	v_cvt_pk_bf16_f32 v148, v16, v32
	ds_write_b32 v151, v148
	v_fmac_f32_e32 v17, v116, v16
	v_fmac_f32_e32 v33, v118, v32
	v_fmac_f32_dpp v17, v16, v122 quad_perm:[1,0,3,2] row_mask:0xf bank_mask:0xf
	v_fmac_f32_dpp v33, v32, v123 quad_perm:[1,0,3,2] row_mask:0xf bank_mask:0xf
	v_cvt_pk_bf16_f32 v149, v17, v33
	ds_write_b32 v151, v149 offset:272
	v_fmac_f32_e32 v18, v116, v17
	v_fmac_f32_e32 v34, v118, v33
	v_fmac_f32_dpp v18, v17, v122 quad_perm:[1,0,3,2] row_mask:0xf bank_mask:0xf
	v_fmac_f32_dpp v34, v33, v123 quad_perm:[1,0,3,2] row_mask:0xf bank_mask:0xf
	v_cvt_pk_bf16_f32 v148, v18, v34
	ds_write_b32 v151, v148 offset:544
	v_fmac_f32_e32 v19, v116, v18
	v_fmac_f32_e32 v35, v118, v34
	v_fmac_f32_dpp v19, v18, v122 quad_perm:[1,0,3,2] row_mask:0xf bank_mask:0xf
	v_fmac_f32_dpp v35, v34, v123 quad_perm:[1,0,3,2] row_mask:0xf bank_mask:0xf
	v_cvt_pk_bf16_f32 v149, v19, v35
	ds_write_b32 v151, v149 offset:816
	v_fmac_f32_e32 v48, v116, v19
	v_fmac_f32_e32 v64, v118, v35
	v_fmac_f32_dpp v48, v19, v122 quad_perm:[1,0,3,2] row_mask:0xf bank_mask:0xf
	v_fmac_f32_dpp v64, v35, v123 quad_perm:[1,0,3,2] row_mask:0xf bank_mask:0xf
	v_cvt_pk_bf16_f32 v148, v48, v64
	ds_write_b32 v151, v148 offset:1088
	v_fmac_f32_e32 v49, v116, v48
	v_fmac_f32_e32 v65, v118, v64
	v_fmac_f32_dpp v49, v48, v122 quad_perm:[1,0,3,2] row_mask:0xf bank_mask:0xf
	v_fmac_f32_dpp v65, v64, v123 quad_perm:[1,0,3,2] row_mask:0xf bank_mask:0xf
	v_cvt_pk_bf16_f32 v149, v49, v65
	ds_write_b32 v151, v149 offset:1360
	v_fmac_f32_e32 v50, v116, v49
	v_fmac_f32_e32 v66, v118, v65
	v_fmac_f32_dpp v50, v49, v122 quad_perm:[1,0,3,2] row_mask:0xf bank_mask:0xf
	v_fmac_f32_dpp v66, v65, v123 quad_perm:[1,0,3,2] row_mask:0xf bank_mask:0xf
	v_cvt_pk_bf16_f32 v148, v50, v66
	ds_write_b32 v151, v148 offset:1632
	v_fmac_f32_e32 v51, v116, v50
	v_fmac_f32_e32 v67, v118, v66
	v_fmac_f32_dpp v51, v50, v122 quad_perm:[1,0,3,2] row_mask:0xf bank_mask:0xf
	v_fmac_f32_dpp v67, v66, v123 quad_perm:[1,0,3,2] row_mask:0xf bank_mask:0xf
	v_cvt_pk_bf16_f32 v149, v51, v67
	ds_write_b32 v151, v149 offset:1904
	v_fmac_f32_e32 v20, v116, v51
	v_fmac_f32_e32 v36, v118, v67
	v_fmac_f32_dpp v20, v51, v122 quad_perm:[1,0,3,2] row_mask:0xf bank_mask:0xf
	v_fmac_f32_dpp v36, v67, v123 quad_perm:[1,0,3,2] row_mask:0xf bank_mask:0xf
	v_cvt_pk_bf16_f32 v148, v20, v36
	ds_write_b32 v151, v148 offset:2176
	v_fmac_f32_e32 v21, v116, v20
	v_fmac_f32_e32 v37, v118, v36
	v_fmac_f32_dpp v21, v20, v122 quad_perm:[1,0,3,2] row_mask:0xf bank_mask:0xf
	v_fmac_f32_dpp v37, v36, v123 quad_perm:[1,0,3,2] row_mask:0xf bank_mask:0xf
	v_cvt_pk_bf16_f32 v149, v21, v37
	ds_write_b32 v151, v149 offset:2448
	v_fmac_f32_e32 v22, v116, v21
	v_fmac_f32_e32 v38, v118, v37
	v_fmac_f32_dpp v22, v21, v122 quad_perm:[1,0,3,2] row_mask:0xf bank_mask:0xf
	v_fmac_f32_dpp v38, v37, v123 quad_perm:[1,0,3,2] row_mask:0xf bank_mask:0xf
	v_cvt_pk_bf16_f32 v148, v22, v38
	ds_write_b32 v151, v148 offset:2720
	v_fmac_f32_e32 v23, v116, v22
	v_fmac_f32_e32 v39, v118, v38
	v_fmac_f32_dpp v23, v22, v122 quad_perm:[1,0,3,2] row_mask:0xf bank_mask:0xf
	v_fmac_f32_dpp v39, v38, v123 quad_perm:[1,0,3,2] row_mask:0xf bank_mask:0xf
	v_cvt_pk_bf16_f32 v149, v23, v39
	ds_write_b32 v151, v149 offset:2992
	v_fmac_f32_e32 v52, v116, v23
	v_fmac_f32_e32 v68, v118, v39
	v_fmac_f32_dpp v52, v23, v122 quad_perm:[1,0,3,2] row_mask:0xf bank_mask:0xf
	v_fmac_f32_dpp v68, v39, v123 quad_perm:[1,0,3,2] row_mask:0xf bank_mask:0xf
	v_cvt_pk_bf16_f32 v148, v52, v68
	ds_write_b32 v151, v148 offset:3264
	v_fmac_f32_e32 v53, v116, v52
	v_fmac_f32_e32 v69, v118, v68
	v_fmac_f32_dpp v53, v52, v122 quad_perm:[1,0,3,2] row_mask:0xf bank_mask:0xf
	v_fmac_f32_dpp v69, v68, v123 quad_perm:[1,0,3,2] row_mask:0xf bank_mask:0xf
	v_cvt_pk_bf16_f32 v149, v53, v69
	ds_write_b32 v151, v149 offset:3536
	v_fmac_f32_e32 v54, v116, v53
	v_fmac_f32_e32 v70, v118, v69
	v_fmac_f32_dpp v54, v53, v122 quad_perm:[1,0,3,2] row_mask:0xf bank_mask:0xf
	v_fmac_f32_dpp v70, v69, v123 quad_perm:[1,0,3,2] row_mask:0xf bank_mask:0xf
	v_cvt_pk_bf16_f32 v148, v54, v70
	ds_write_b32 v151, v148 offset:3808
	v_fmac_f32_e32 v55, v116, v54
	v_fmac_f32_e32 v71, v118, v70
	v_fmac_f32_dpp v55, v54, v122 quad_perm:[1,0,3,2] row_mask:0xf bank_mask:0xf
	v_fmac_f32_dpp v71, v70, v123 quad_perm:[1,0,3,2] row_mask:0xf bank_mask:0xf
	v_cvt_pk_bf16_f32 v149, v55, v71
	ds_write_b32 v151, v149 offset:4080
	v_fmac_f32_e32 v24, v116, v55
	v_fmac_f32_e32 v40, v118, v71
	v_fmac_f32_dpp v24, v55, v122 quad_perm:[1,0,3,2] row_mask:0xf bank_mask:0xf
	v_fmac_f32_dpp v40, v71, v123 quad_perm:[1,0,3,2] row_mask:0xf bank_mask:0xf
	v_cvt_pk_bf16_f32 v148, v24, v40
	ds_write_b32 v151, v148 offset:4352
	v_fmac_f32_e32 v25, v116, v24
	v_fmac_f32_e32 v41, v118, v40
	v_fmac_f32_dpp v25, v24, v122 quad_perm:[1,0,3,2] row_mask:0xf bank_mask:0xf
	v_fmac_f32_dpp v41, v40, v123 quad_perm:[1,0,3,2] row_mask:0xf bank_mask:0xf
	v_cvt_pk_bf16_f32 v149, v25, v41
	ds_write_b32 v151, v149 offset:4624
	v_fmac_f32_e32 v26, v116, v25
	v_fmac_f32_e32 v42, v118, v41
	v_fmac_f32_dpp v26, v25, v122 quad_perm:[1,0,3,2] row_mask:0xf bank_mask:0xf
	v_fmac_f32_dpp v42, v41, v123 quad_perm:[1,0,3,2] row_mask:0xf bank_mask:0xf
	v_cvt_pk_bf16_f32 v148, v26, v42
	ds_write_b32 v151, v148 offset:4896
	v_fmac_f32_e32 v27, v116, v26
	v_fmac_f32_e32 v43, v118, v42
	v_fmac_f32_dpp v27, v26, v122 quad_perm:[1,0,3,2] row_mask:0xf bank_mask:0xf
	v_fmac_f32_dpp v43, v42, v123 quad_perm:[1,0,3,2] row_mask:0xf bank_mask:0xf
	v_cvt_pk_bf16_f32 v149, v27, v43
	ds_write_b32 v151, v149 offset:5168
	v_fmac_f32_e32 v56, v116, v27
	v_fmac_f32_e32 v72, v118, v43
	v_fmac_f32_dpp v56, v27, v122 quad_perm:[1,0,3,2] row_mask:0xf bank_mask:0xf
	v_fmac_f32_dpp v72, v43, v123 quad_perm:[1,0,3,2] row_mask:0xf bank_mask:0xf
	v_cvt_pk_bf16_f32 v148, v56, v72
	ds_write_b32 v151, v148 offset:5440
	v_fmac_f32_e32 v57, v116, v56
	v_fmac_f32_e32 v73, v118, v72
	v_fmac_f32_dpp v57, v56, v122 quad_perm:[1,0,3,2] row_mask:0xf bank_mask:0xf
	v_fmac_f32_dpp v73, v72, v123 quad_perm:[1,0,3,2] row_mask:0xf bank_mask:0xf
	v_cvt_pk_bf16_f32 v149, v57, v73
	ds_write_b32 v151, v149 offset:5712
	v_fmac_f32_e32 v58, v116, v57
	v_fmac_f32_e32 v74, v118, v73
	v_fmac_f32_dpp v58, v57, v122 quad_perm:[1,0,3,2] row_mask:0xf bank_mask:0xf
	v_fmac_f32_dpp v74, v73, v123 quad_perm:[1,0,3,2] row_mask:0xf bank_mask:0xf
	v_cvt_pk_bf16_f32 v148, v58, v74
	ds_write_b32 v151, v148 offset:5984
	v_fmac_f32_e32 v59, v116, v58
	v_fmac_f32_e32 v75, v118, v74
	v_fmac_f32_dpp v59, v58, v122 quad_perm:[1,0,3,2] row_mask:0xf bank_mask:0xf
	v_fmac_f32_dpp v75, v74, v123 quad_perm:[1,0,3,2] row_mask:0xf bank_mask:0xf
	v_cvt_pk_bf16_f32 v149, v59, v75
	ds_write_b32 v151, v149 offset:6256
	v_fmac_f32_e32 v28, v116, v59
	v_fmac_f32_e32 v44, v118, v75
	v_fmac_f32_dpp v28, v59, v122 quad_perm:[1,0,3,2] row_mask:0xf bank_mask:0xf
	v_fmac_f32_dpp v44, v75, v123 quad_perm:[1,0,3,2] row_mask:0xf bank_mask:0xf
	v_cvt_pk_bf16_f32 v148, v28, v44
	ds_write_b32 v151, v148 offset:6528
	v_fmac_f32_e32 v29, v116, v28
	v_fmac_f32_e32 v45, v118, v44
	v_fmac_f32_dpp v29, v28, v122 quad_perm:[1,0,3,2] row_mask:0xf bank_mask:0xf
	v_fmac_f32_dpp v45, v44, v123 quad_perm:[1,0,3,2] row_mask:0xf bank_mask:0xf
	v_cvt_pk_bf16_f32 v149, v29, v45
	ds_write_b32 v151, v149 offset:6800
	v_fmac_f32_e32 v30, v116, v29
	v_fmac_f32_e32 v46, v118, v45
	v_fmac_f32_dpp v30, v29, v122 quad_perm:[1,0,3,2] row_mask:0xf bank_mask:0xf
	v_fmac_f32_dpp v46, v45, v123 quad_perm:[1,0,3,2] row_mask:0xf bank_mask:0xf
	v_cvt_pk_bf16_f32 v148, v30, v46
	ds_write_b32 v151, v148 offset:7072
	v_fmac_f32_e32 v31, v116, v30
	v_fmac_f32_e32 v47, v118, v46
	v_fmac_f32_dpp v31, v30, v122 quad_perm:[1,0,3,2] row_mask:0xf bank_mask:0xf
	v_fmac_f32_dpp v47, v46, v123 quad_perm:[1,0,3,2] row_mask:0xf bank_mask:0xf
	v_cvt_pk_bf16_f32 v149, v31, v47
	ds_write_b32 v151, v149 offset:7344
	v_fmac_f32_e32 v60, v116, v31
	v_fmac_f32_e32 v76, v118, v47
	v_fmac_f32_dpp v60, v31, v122 quad_perm:[1,0,3,2] row_mask:0xf bank_mask:0xf
	v_fmac_f32_dpp v76, v47, v123 quad_perm:[1,0,3,2] row_mask:0xf bank_mask:0xf
	v_cvt_pk_bf16_f32 v148, v60, v76
	ds_write_b32 v151, v148 offset:7616
	v_fmac_f32_e32 v61, v116, v60
	v_fmac_f32_e32 v77, v118, v76
	v_fmac_f32_dpp v61, v60, v122 quad_perm:[1,0,3,2] row_mask:0xf bank_mask:0xf
	v_fmac_f32_dpp v77, v76, v123 quad_perm:[1,0,3,2] row_mask:0xf bank_mask:0xf
	v_cvt_pk_bf16_f32 v149, v61, v77
	ds_write_b32 v151, v149 offset:7888
	v_fmac_f32_e32 v62, v116, v61
	v_fmac_f32_e32 v78, v118, v77
	v_fmac_f32_dpp v62, v61, v122 quad_perm:[1,0,3,2] row_mask:0xf bank_mask:0xf
	v_fmac_f32_dpp v78, v77, v123 quad_perm:[1,0,3,2] row_mask:0xf bank_mask:0xf
	v_cvt_pk_bf16_f32 v148, v62, v78
	ds_write_b32 v151, v148 offset:8160
	v_fmac_f32_e32 v63, v116, v62
	v_fmac_f32_e32 v79, v118, v78
	v_fmac_f32_dpp v63, v62, v122 quad_perm:[1,0,3,2] row_mask:0xf bank_mask:0xf
	v_fmac_f32_dpp v79, v78, v123 quad_perm:[1,0,3,2] row_mask:0xf bank_mask:0xf
	v_cvt_pk_bf16_f32 v149, v63, v79
	ds_write_b32 v151, v149 offset:8432
	v_mov_b32_e32 v120, v63
	v_mov_b32_e32 v121, v79
	ds_read_b128 v[124:127], v152
	ds_read_b128 v[128:131], v152 offset:64
	ds_read_b128 v[132:135], v152 offset:128
	ds_read_b128 v[136:139], v152 offset:192
	s_waitcnt lgkmcnt(3)
	v_mfma_f32_16x16x32_bf16 v[140:143], v[100:103], v[124:127], 0
	s_waitcnt lgkmcnt(2)
	v_mfma_f32_16x16x32_bf16 v[140:143], v[104:107], v[128:131], v[140:143]
	s_waitcnt lgkmcnt(1)
	v_mfma_f32_16x16x32_bf16 v[140:143], v[108:111], v[132:135], v[140:143]
	s_waitcnt lgkmcnt(0)
	v_mfma_f32_16x16x32_bf16 v[140:143], v[112:115], v[136:139], v[140:143]
	s_nop 9
	global_store_dwordx4 v153, v[140:143], s[12:13]
	s_nop 1
	ds_read_b128 v[124:127], v152 offset:4352
	ds_read_b128 v[128:131], v152 offset:4416
	ds_read_b128 v[132:135], v152 offset:4480
	ds_read_b128 v[136:139], v152 offset:4544
	s_waitcnt lgkmcnt(3)
	v_mfma_f32_16x16x32_bf16 v[140:143], v[100:103], v[124:127], 0
	s_waitcnt lgkmcnt(2)
	v_mfma_f32_16x16x32_bf16 v[140:143], v[104:107], v[128:131], v[140:143]
	s_waitcnt lgkmcnt(1)
	v_mfma_f32_16x16x32_bf16 v[140:143], v[108:111], v[132:135], v[140:143]
	s_waitcnt lgkmcnt(0)
	v_mfma_f32_16x16x32_bf16 v[140:143], v[112:115], v[136:139], v[140:143]
	s_nop 9
	global_store_dwordx4 v157, v[140:143], s[12:13]
	s_nop 1
	s_add_u32 s12, s12, 2048
	s_addc_u32 s13, s13, 0
	s_add_u32 s14, s14, 2
	s_cmp_lt_u32 s14, 16
	s_cbranch_scc1 .Lssm_tileA_d0m0
	s_waitcnt vmcnt(0) lgkmcnt(0)
	s_lshr_b32 s21, s89, 1
	s_lshl_b32 s21, s21, 2
	s_add_u32 s37, s21, 0x21000
	v_mov_b32_e32 v182, s37
	v_mov_b32_e32 v183, 1
	v_cmp_eq_u32_e32 vcc, 0, v191
	s_and_saveexec_b64 s[0:1], vcc
	ds_add_u32 v182, v183
	s_mov_b64 exec, s[0:1]
	s_waitcnt lgkmcnt(0)
	s_mov_b32 s38, 0

.Lssm_spin_done_d0m0:
	s_mov_b64 s[42:43], s[6:7]
	s_add_u32 s42, s42, 32768
	s_addc_u32 s43, s43, 0
	s_lshl_b32 s31, s25, 11
	s_lshl_b32 s29, s24, 5
	s_add_u32 s31, s31, s29
	s_add_u32 s31, s31, 344981504
	s_add_u32 s12, s62, s31
	s_addc_u32 s13, s63, 0
	s_mov_b64 s[64:65], s[34:35]
	s_sub_u32 s64, s64, 196608
	s_subb_u32 s65, s65, 0
	global_load_dwordx4 v[6:9], v153, s[42:43]
	global_load_dwordx4 v[10:13], v157, s[42:43]
	s_add_u32 s42, s42, 2048
	s_addc_u32 s43, s43, 0
	s_waitcnt vmcnt(0)
.Lssm_tileB_d0m0:
	s_waitcnt vmcnt(7)
	v_mfma_f32_32x32x16_bf16 v[16:31], v[80:83], v[84:87], 0
	v_mfma_f32_32x32x16_bf16 v[32:47], v[80:83], v[88:91], 0
	v_mfma_f32_32x32x16_bf16 v[48:63], v[80:83], v[92:95], 0
	v_mfma_f32_32x32x16_bf16 v[64:79], v[80:83], v[96:99], 0
	ds_write_b128 v162, v[80:83]
	global_load_dwordx4 v[172:175], v153, s[42:43]
	global_load_dwordx4 v[176:179], v157, s[42:43]
	s_add_u32 s42, s42, 2048
	s_addc_u32 s43, s43, 0
	s_nop 11
	global_load_dwordx4 v[80:83], v150, s[10:11]
	s_add_u32 s34, s34, 196608
	s_addc_u32 s35, s35, 0
	s_add_u32 s10, s10, 196608
	s_addc_u32 s11, s11, 0
	v_permlane32_swap_b32_e32 v16, v48
	v_permlane32_swap_b32_e32 v17, v49
	v_permlane32_swap_b32_e32 v18, v50
	v_permlane32_swap_b32_e32 v19, v51
	v_permlane32_swap_b32_e32 v20, v52
	v_permlane32_swap_b32_e32 v21, v53
	v_permlane32_swap_b32_e32 v22, v54
	v_permlane32_swap_b32_e32 v23, v55
	v_permlane32_swap_b32_e32 v24, v56
	v_permlane32_swap_b32_e32 v25, v57
	v_permlane32_swap_b32_e32 v26, v58
	v_permlane32_swap_b32_e32 v27, v59
	v_permlane32_swap_b32_e32 v28, v60
	v_permlane32_swap_b32_e32 v29, v61
	v_permlane32_swap_b32_e32 v30, v62
	v_permlane32_swap_b32_e32 v31, v63
	v_permlane32_swap_b32_e32 v32, v64
	v_permlane32_swap_b32_e32 v33, v65
	v_permlane32_swap_b32_e32 v34, v66
	v_permlane32_swap_b32_e32 v35, v67
	v_permlane32_swap_b32_e32 v36, v68
	v_permlane32_swap_b32_e32 v37, v69
	v_permlane32_swap_b32_e32 v38, v70
	v_permlane32_swap_b32_e32 v39, v71
	v_permlane32_swap_b32_e32 v40, v72
	v_permlane32_swap_b32_e32 v41, v73
	v_permlane32_swap_b32_e32 v42, v74
	v_permlane32_swap_b32_e32 v43, v75
	v_permlane32_swap_b32_e32 v44, v76
	v_permlane32_swap_b32_e32 v45, v77
	v_permlane32_swap_b32_e32 v46, v78
	v_permlane32_swap_b32_e32 v47, v79
	v_fmac_f32_e32 v16, v116, v120
	v_fmac_f32_e32 v32, v118, v121
	v_fmac_f32_dpp v16, v120, v122 quad_perm:[1,0,3,2] row_mask:0xf bank_mask:0xf
	v_fmac_f32_dpp v32, v121, v123 quad_perm:[1,0,3,2] row_mask:0xf bank_mask:0xf
	v_cvt_pk_bf16_f32 v148, v16, v32
	ds_write_b32 v151, v148
	v_fmac_f32_e32 v17, v116, v16
	v_fmac_f32_e32 v33, v118, v32
	v_fmac_f32_dpp v17, v16, v122 quad_perm:[1,0,3,2] row_mask:0xf bank_mask:0xf
	v_fmac_f32_dpp v33, v32, v123 quad_perm:[1,0,3,2] row_mask:0xf bank_mask:0xf
	v_cvt_pk_bf16_f32 v149, v17, v33
	ds_write_b32 v151, v149 offset:272
	v_fmac_f32_e32 v18, v116, v17
	v_fmac_f32_e32 v34, v118, v33
	v_fmac_f32_dpp v18, v17, v122 quad_perm:[1,0,3,2] row_mask:0xf bank_mask:0xf
	v_fmac_f32_dpp v34, v33, v123 quad_perm:[1,0,3,2] row_mask:0xf bank_mask:0xf
	v_cvt_pk_bf16_f32 v148, v18, v34
	ds_write_b32 v151, v148 offset:544
	v_fmac_f32_e32 v19, v116, v18
	v_fmac_f32_e32 v35, v118, v34
	v_fmac_f32_dpp v19, v18, v122 quad_perm:[1,0,3,2] row_mask:0xf bank_mask:0xf
	v_fmac_f32_dpp v35, v34, v123 quad_perm:[1,0,3,2] row_mask:0xf bank_mask:0xf
	v_cvt_pk_bf16_f32 v149, v19, v35
	ds_write_b32 v151, v149 offset:816
	v_fmac_f32_e32 v48, v116, v19
	v_fmac_f32_e32 v64, v118, v35
	v_fmac_f32_dpp v48, v19, v122 quad_perm:[1,0,3,2] row_mask:0xf bank_mask:0xf
	v_fmac_f32_dpp v64, v35, v123 quad_perm:[1,0,3,2] row_mask:0xf bank_mask:0xf
	v_cvt_pk_bf16_f32 v148, v48, v64
	ds_write_b32 v151, v148 offset:1088
	v_fmac_f32_e32 v49, v116, v48
	v_fmac_f32_e32 v65, v118, v64
	v_fmac_f32_dpp v49, v48, v122 quad_perm:[1,0,3,2] row_mask:0xf bank_mask:0xf
	v_fmac_f32_dpp v65, v64, v123 quad_perm:[1,0,3,2] row_mask:0xf bank_mask:0xf
	v_cvt_pk_bf16_f32 v149, v49, v65
	ds_write_b32 v151, v149 offset:1360
	v_fmac_f32_e32 v50, v116, v49
	v_fmac_f32_e32 v66, v118, v65
	v_fmac_f32_dpp v50, v49, v122 quad_perm:[1,0,3,2] row_mask:0xf bank_mask:0xf
	v_fmac_f32_dpp v66, v65, v123 quad_perm:[1,0,3,2] row_mask:0xf bank_mask:0xf
	v_cvt_pk_bf16_f32 v148, v50, v66
	ds_write_b32 v151, v148 offset:1632
	v_fmac_f32_e32 v51, v116, v50
	v_fmac_f32_e32 v67, v118, v66
	v_fmac_f32_dpp v51, v50, v122 quad_perm:[1,0,3,2] row_mask:0xf bank_mask:0xf
	v_fmac_f32_dpp v67, v66, v123 quad_perm:[1,0,3,2] row_mask:0xf bank_mask:0xf
	v_cvt_pk_bf16_f32 v149, v51, v67
	ds_write_b32 v151, v149 offset:1904
	v_fmac_f32_e32 v20, v116, v51
	v_fmac_f32_e32 v36, v118, v67
	v_fmac_f32_dpp v20, v51, v122 quad_perm:[1,0,3,2] row_mask:0xf bank_mask:0xf
	v_fmac_f32_dpp v36, v67, v123 quad_perm:[1,0,3,2] row_mask:0xf bank_mask:0xf
	v_cvt_pk_bf16_f32 v148, v20, v36
	ds_write_b32 v151, v148 offset:2176
	v_fmac_f32_e32 v21, v116, v20
	v_fmac_f32_e32 v37, v118, v36
	v_fmac_f32_dpp v21, v20, v122 quad_perm:[1,0,3,2] row_mask:0xf bank_mask:0xf
	v_fmac_f32_dpp v37, v36, v123 quad_perm:[1,0,3,2] row_mask:0xf bank_mask:0xf
	v_cvt_pk_bf16_f32 v149, v21, v37
	ds_write_b32 v151, v149 offset:2448
	v_fmac_f32_e32 v22, v116, v21
	v_fmac_f32_e32 v38, v118, v37
	v_fmac_f32_dpp v22, v21, v122 quad_perm:[1,0,3,2] row_mask:0xf bank_mask:0xf
	v_fmac_f32_dpp v38, v37, v123 quad_perm:[1,0,3,2] row_mask:0xf bank_mask:0xf
	v_cvt_pk_bf16_f32 v148, v22, v38
	ds_write_b32 v151, v148 offset:2720
	v_fmac_f32_e32 v23, v116, v22
	v_fmac_f32_e32 v39, v118, v38
	v_fmac_f32_dpp v23, v22, v122 quad_perm:[1,0,3,2] row_mask:0xf bank_mask:0xf
	v_fmac_f32_dpp v39, v38, v123 quad_perm:[1,0,3,2] row_mask:0xf bank_mask:0xf
	v_cvt_pk_bf16_f32 v149, v23, v39
	ds_write_b32 v151, v149 offset:2992
	v_fmac_f32_e32 v52, v116, v23
	v_fmac_f32_e32 v68, v118, v39
	v_fmac_f32_dpp v52, v23, v122 quad_perm:[1,0,3,2] row_mask:0xf bank_mask:0xf
	v_fmac_f32_dpp v68, v39, v123 quad_perm:[1,0,3,2] row_mask:0xf bank_mask:0xf
	v_cvt_pk_bf16_f32 v148, v52, v68
	ds_write_b32 v151, v148 offset:3264
	v_fmac_f32_e32 v53, v116, v52
	v_fmac_f32_e32 v69, v118, v68
	v_fmac_f32_dpp v53, v52, v122 quad_perm:[1,0,3,2] row_mask:0xf bank_mask:0xf
	v_fmac_f32_dpp v69, v68, v123 quad_perm:[1,0,3,2] row_mask:0xf bank_mask:0xf
	v_cvt_pk_bf16_f32 v149, v53, v69
	ds_write_b32 v151, v149 offset:3536
	v_fmac_f32_e32 v54, v116, v53
	v_fmac_f32_e32 v70, v118, v69
	v_fmac_f32_dpp v54, v53, v122 quad_perm:[1,0,3,2] row_mask:0xf bank_mask:0xf
	v_fmac_f32_dpp v70, v69, v123 quad_perm:[1,0,3,2] row_mask:0xf bank_mask:0xf
	v_cvt_pk_bf16_f32 v148, v54, v70
	ds_write_b32 v151, v148 offset:3808
	v_fmac_f32_e32 v55, v116, v54
	v_fmac_f32_e32 v71, v118, v70
	v_fmac_f32_dpp v55, v54, v122 quad_perm:[1,0,3,2] row_mask:0xf bank_mask:0xf
	v_fmac_f32_dpp v71, v70, v123 quad_perm:[1,0,3,2] row_mask:0xf bank_mask:0xf
	v_cvt_pk_bf16_f32 v149, v55, v71
	ds_write_b32 v151, v149 offset:4080
	v_fmac_f32_e32 v24, v116, v55
	v_fmac_f32_e32 v40, v118, v71
	v_fmac_f32_dpp v24, v55, v122 quad_perm:[1,0,3,2] row_mask:0xf bank_mask:0xf
	v_fmac_f32_dpp v40, v71, v123 quad_perm:[1,0,3,2] row_mask:0xf bank_mask:0xf
	v_cvt_pk_bf16_f32 v148, v24, v40
	ds_write_b32 v151, v148 offset:4352
	v_fmac_f32_e32 v25, v116, v24
	v_fmac_f32_e32 v41, v118, v40
	v_fmac_f32_dpp v25, v24, v122 quad_perm:[1,0,3,2] row_mask:0xf bank_mask:0xf
	v_fmac_f32_dpp v41, v40, v123 quad_perm:[1,0,3,2] row_mask:0xf bank_mask:0xf
	v_cvt_pk_bf16_f32 v149, v25, v41
	ds_write_b32 v151, v149 offset:4624
	v_fmac_f32_e32 v26, v116, v25
	v_fmac_f32_e32 v42, v118, v41
	v_fmac_f32_dpp v26, v25, v122 quad_perm:[1,0,3,2] row_mask:0xf bank_mask:0xf
	v_fmac_f32_dpp v42, v41, v123 quad_perm:[1,0,3,2] row_mask:0xf bank_mask:0xf
	v_cvt_pk_bf16_f32 v148, v26, v42
	ds_write_b32 v151, v148 offset:4896
	v_fmac_f32_e32 v27, v116, v26
	v_fmac_f32_e32 v43, v118, v42
	v_fmac_f32_dpp v27, v26, v122 quad_perm:[1,0,3,2] row_mask:0xf bank_mask:0xf
	v_fmac_f32_dpp v43, v42, v123 quad_perm:[1,0,3,2] row_mask:0xf bank_mask:0xf
	v_cvt_pk_bf16_f32 v149, v27, v43
	ds_write_b32 v151, v149 offset:5168
	v_fmac_f32_e32 v56, v116, v27
	v_fmac_f32_e32 v72, v118, v43
	v_fmac_f32_dpp v56, v27, v122 quad_perm:[1,0,3,2] row_mask:0xf bank_mask:0xf
	v_fmac_f32_dpp v72, v43, v123 quad_perm:[1,0,3,2] row_mask:0xf bank_mask:0xf
	v_cvt_pk_bf16_f32 v148, v56, v72
	ds_write_b32 v151, v148 offset:5440
	v_fmac_f32_e32 v57, v116, v56
	v_fmac_f32_e32 v73, v118, v72
	v_fmac_f32_dpp v57, v56, v122 quad_perm:[1,0,3,2] row_mask:0xf bank_mask:0xf
	v_fmac_f32_dpp v73, v72, v123 quad_perm:[1,0,3,2] row_mask:0xf bank_mask:0xf
	v_cvt_pk_bf16_f32 v149, v57, v73
	ds_write_b32 v151, v149 offset:5712
	v_fmac_f32_e32 v58, v116, v57
	v_fmac_f32_e32 v74, v118, v73
	v_fmac_f32_dpp v58, v57, v122 quad_perm:[1,0,3,2] row_mask:0xf bank_mask:0xf
	v_fmac_f32_dpp v74, v73, v123 quad_perm:[1,0,3,2] row_mask:0xf bank_mask:0xf
	v_cvt_pk_bf16_f32 v148, v58, v74
	ds_write_b32 v151, v148 offset:5984
	v_fmac_f32_e32 v59, v116, v58
	v_fmac_f32_e32 v75, v118, v74
	v_fmac_f32_dpp v59, v58, v122 quad_perm:[1,0,3,2] row_mask:0xf bank_mask:0xf
	v_fmac_f32_dpp v75, v74, v123 quad_perm:[1,0,3,2] row_mask:0xf bank_mask:0xf
	v_cvt_pk_bf16_f32 v149, v59, v75
	ds_write_b32 v151, v149 offset:6256
	v_fmac_f32_e32 v28, v116, v59
	v_fmac_f32_e32 v44, v118, v75
	v_fmac_f32_dpp v28, v59, v122 quad_perm:[1,0,3,2] row_mask:0xf bank_mask:0xf
	v_fmac_f32_dpp v44, v75, v123 quad_perm:[1,0,3,2] row_mask:0xf bank_mask:0xf
	v_cvt_pk_bf16_f32 v148, v28, v44
	ds_write_b32 v151, v148 offset:6528
	v_fmac_f32_e32 v29, v116, v28
	v_fmac_f32_e32 v45, v118, v44
	v_fmac_f32_dpp v29, v28, v122 quad_perm:[1,0,3,2] row_mask:0xf bank_mask:0xf
	v_fmac_f32_dpp v45, v44, v123 quad_perm:[1,0,3,2] row_mask:0xf bank_mask:0xf
	v_cvt_pk_bf16_f32 v149, v29, v45
	ds_write_b32 v151, v149 offset:6800
	v_fmac_f32_e32 v30, v116, v29
	v_fmac_f32_e32 v46, v118, v45
	v_fmac_f32_dpp v30, v29, v122 quad_perm:[1,0,3,2] row_mask:0xf bank_mask:0xf
	v_fmac_f32_dpp v46, v45, v123 quad_perm:[1,0,3,2] row_mask:0xf bank_mask:0xf
	v_cvt_pk_bf16_f32 v148, v30, v46
	ds_write_b32 v151, v148 offset:7072
	v_fmac_f32_e32 v31, v116, v30
	v_fmac_f32_e32 v47, v118, v46
	v_fmac_f32_dpp v31, v30, v122 quad_perm:[1,0,3,2] row_mask:0xf bank_mask:0xf
	v_fmac_f32_dpp v47, v46, v123 quad_perm:[1,0,3,2] row_mask:0xf bank_mask:0xf
	v_cvt_pk_bf16_f32 v149, v31, v47
	ds_write_b32 v151, v149 offset:7344
	v_fmac_f32_e32 v60, v116, v31
	v_fmac_f32_e32 v76, v118, v47
	v_fmac_f32_dpp v60, v31, v122 quad_perm:[1,0,3,2] row_mask:0xf bank_mask:0xf
	v_fmac_f32_dpp v76, v47, v123 quad_perm:[1,0,3,2] row_mask:0xf bank_mask:0xf
	v_cvt_pk_bf16_f32 v148, v60, v76
	ds_write_b32 v151, v148 offset:7616
	v_fmac_f32_e32 v61, v116, v60
	v_fmac_f32_e32 v77, v118, v76
	v_fmac_f32_dpp v61, v60, v122 quad_perm:[1,0,3,2] row_mask:0xf bank_mask:0xf
	v_fmac_f32_dpp v77, v76, v123 quad_perm:[1,0,3,2] row_mask:0xf bank_mask:0xf
	v_cvt_pk_bf16_f32 v149, v61, v77
	ds_write_b32 v151, v149 offset:7888
	v_fmac_f32_e32 v62, v116, v61
	v_fmac_f32_e32 v78, v118, v77
	v_fmac_f32_dpp v62, v61, v122 quad_perm:[1,0,3,2] row_mask:0xf bank_mask:0xf
	v_fmac_f32_dpp v78, v77, v123 quad_perm:[1,0,3,2] row_mask:0xf bank_mask:0xf
	v_cvt_pk_bf16_f32 v148, v62, v78
	ds_write_b32 v151, v148 offset:8160
	v_fmac_f32_e32 v63, v116, v62
	v_fmac_f32_e32 v79, v118, v78
	v_fmac_f32_dpp v63, v62, v122 quad_perm:[1,0,3,2] row_mask:0xf bank_mask:0xf
	v_fmac_f32_dpp v79, v78, v123 quad_perm:[1,0,3,2] row_mask:0xf bank_mask:0xf
	v_cvt_pk_bf16_f32 v149, v63, v79
	ds_write_b32 v151, v149 offset:8432
	v_mov_b32_e32 v120, v63
	v_mov_b32_e32 v121, v79
	ds_read_b128 v[124:127], v152
	ds_read_b128 v[128:131], v152 offset:64
	ds_read_b128 v[132:135], v152 offset:128
	ds_read_b128 v[136:139], v152 offset:192
	ds_read_b64 v[160:161], v163
	s_waitcnt lgkmcnt(4)
	v_mfma_f32_16x16x32_bf16 v[140:143], v[100:103], v[124:127], 0
	s_waitcnt lgkmcnt(3)
	v_mfma_f32_16x16x32_bf16 v[140:143], v[104:107], v[128:131], v[140:143]
	s_waitcnt lgkmcnt(2)
	v_mfma_f32_16x16x32_bf16 v[140:143], v[108:111], v[132:135], v[140:143]
	s_waitcnt lgkmcnt(1)
	v_mfma_f32_16x16x32_bf16 v[140:143], v[112:115], v[136:139], v[140:143]
	s_nop 9
	s_waitcnt vmcnt(7) lgkmcnt(0)
	v_add_f32_e32 v182, v6, v140
	v_add_f32_e32 v183, v7, v141
	v_add_f32_e32 v184, v8, v142
	v_add_f32_e32 v185, v9, v143
	v_lshlrev_b32_e32 v186, 16, v160
	v_and_b32_e32 v187, 0xffff0000, v160
	v_lshlrev_b32_e32 v188, 16, v161
	v_and_b32_e32 v189, 0xffff0000, v161
	v_fmac_f32_e32 v182, v164, v186
	v_fmac_f32_e32 v183, v165, v187
	v_fmac_f32_e32 v184, v166, v188
	v_fmac_f32_e32 v185, v167, v189
	v_mul_f32_e32 v186, 0x3d372713, v182
	v_mul_f32_e32 v187, 0x3d372713, v183
	v_mul_f32_e32 v188, 0x3d372713, v184
	v_mul_f32_e32 v189, 0x3d372713, v185
	v_mul_f32_e32 v186, v182, v186
	v_mul_f32_e32 v187, v183, v187
	v_mul_f32_e32 v188, v184, v188
	v_mul_f32_e32 v189, v185, v189
	v_fma_f32 v186, v182, v186, v182
	v_fma_f32 v187, v183, v187, v183
	v_fma_f32 v188, v184, v188, v184
	v_fma_f32 v189, v185, v189, v185
	v_mul_f32_e32 v186, 0xbfcc422a, v186
	v_mul_f32_e32 v187, 0xbfcc422a, v187
	v_mul_f32_e32 v188, 0xbfcc422a, v188
	v_mul_f32_e32 v189, 0xbfcc422a, v189
	v_mul_f32_e32 v186, 0x3fb8aa3b, v186
	v_mul_f32_e32 v187, 0x3fb8aa3b, v187
	v_mul_f32_e32 v188, 0x3fb8aa3b, v188
	v_mul_f32_e32 v189, 0x3fb8aa3b, v189
	v_exp_f32_e32 v186, v186
	v_exp_f32_e32 v187, v187
	v_exp_f32_e32 v188, v188
	v_exp_f32_e32 v189, v189
	v_add_f32_e32 v186, 1.0, v186
	v_add_f32_e32 v187, 1.0, v187
	v_add_f32_e32 v188, 1.0, v188
	v_add_f32_e32 v189, 1.0, v189
	v_rcp_f32_e32 v186, v186
	v_rcp_f32_e32 v187, v187
	v_rcp_f32_e32 v188, v188
	v_rcp_f32_e32 v189, v189
	v_mul_f32_e32 v182, v182, v186
	v_mul_f32_e32 v183, v183, v187
	v_mul_f32_e32 v184, v184, v188
	v_mul_f32_e32 v185, v185, v189
	v_cvt_pk_bf16_f32 v148, v182, v183
	v_cvt_pk_bf16_f32 v149, v184, v185
	global_store_dwordx2 v156, v[148:149], s[12:13]
	ds_read_b128 v[124:127], v152 offset:4352
	ds_read_b128 v[128:131], v152 offset:4416
	ds_read_b128 v[132:135], v152 offset:4480
	ds_read_b128 v[136:139], v152 offset:4544
	ds_read_b64 v[160:161], v163 offset:512
	s_waitcnt lgkmcnt(4)
	v_mfma_f32_16x16x32_bf16 v[140:143], v[100:103], v[124:127], 0
	s_waitcnt lgkmcnt(3)
	v_mfma_f32_16x16x32_bf16 v[140:143], v[104:107], v[128:131], v[140:143]
	s_waitcnt lgkmcnt(2)
	v_mfma_f32_16x16x32_bf16 v[140:143], v[108:111], v[132:135], v[140:143]
	s_waitcnt lgkmcnt(1)
	v_mfma_f32_16x16x32_bf16 v[140:143], v[112:115], v[136:139], v[140:143]
	s_nop 9
	s_waitcnt vmcnt(7) lgkmcnt(0)
	v_add_f32_e32 v182, v10, v140
	v_add_f32_e32 v183, v11, v141
	v_add_f32_e32 v184, v12, v142
	v_add_f32_e32 v185, v13, v143
	v_lshlrev_b32_e32 v186, 16, v160
	v_and_b32_e32 v187, 0xffff0000, v160
	v_lshlrev_b32_e32 v188, 16, v161
	v_and_b32_e32 v189, 0xffff0000, v161
	v_fmac_f32_e32 v182, v164, v186
	v_fmac_f32_e32 v183, v165, v187
	v_fmac_f32_e32 v184, v166, v188
	v_fmac_f32_e32 v185, v167, v189
	v_mul_f32_e32 v186, 0x3d372713, v182
	v_mul_f32_e32 v187, 0x3d372713, v183
	v_mul_f32_e32 v188, 0x3d372713, v184
	v_mul_f32_e32 v189, 0x3d372713, v185
	v_mul_f32_e32 v186, v182, v186
	v_mul_f32_e32 v187, v183, v187
	v_mul_f32_e32 v188, v184, v188
	v_mul_f32_e32 v189, v185, v189
	v_fma_f32 v186, v182, v186, v182
	v_fma_f32 v187, v183, v187, v183
	v_fma_f32 v188, v184, v188, v184
	v_fma_f32 v189, v185, v189, v185
	v_mul_f32_e32 v186, 0xbfcc422a, v186
	v_mul_f32_e32 v187, 0xbfcc422a, v187
	v_mul_f32_e32 v188, 0xbfcc422a, v188
	v_mul_f32_e32 v189, 0xbfcc422a, v189
	v_mul_f32_e32 v186, 0x3fb8aa3b, v186
	v_mul_f32_e32 v187, 0x3fb8aa3b, v187
	v_mul_f32_e32 v188, 0x3fb8aa3b, v188
	v_mul_f32_e32 v189, 0x3fb8aa3b, v189
	v_exp_f32_e32 v186, v186
	v_exp_f32_e32 v187, v187
	v_exp_f32_e32 v188, v188
	v_exp_f32_e32 v189, v189
	v_add_f32_e32 v186, 1.0, v186
	v_add_f32_e32 v187, 1.0, v187
	v_add_f32_e32 v188, 1.0, v188
	v_add_f32_e32 v189, 1.0, v189
	v_rcp_f32_e32 v186, v186
	v_rcp_f32_e32 v187, v187
	v_rcp_f32_e32 v188, v188
	v_rcp_f32_e32 v189, v189
	v_mul_f32_e32 v182, v182, v186
	v_mul_f32_e32 v183, v183, v187
	v_mul_f32_e32 v184, v184, v188
	v_mul_f32_e32 v185, v185, v189
	v_cvt_pk_bf16_f32 v148, v182, v183
	v_cvt_pk_bf16_f32 v149, v184, v185
	global_store_dwordx2 v159, v[148:149], s[12:13]
	s_add_u32 s12, s12, 65536
	s_addc_u32 s13, s13, 0
	s_waitcnt vmcnt(7)
	v_mfma_f32_32x32x16_bf16 v[16:31], v[144:147], v[84:87], 0
	v_mfma_f32_32x32x16_bf16 v[32:47], v[144:147], v[88:91], 0
	v_mfma_f32_32x32x16_bf16 v[48:63], v[144:147], v[92:95], 0
	v_mfma_f32_32x32x16_bf16 v[64:79], v[144:147], v[96:99], 0
	ds_write_b128 v162, v[144:147]
	global_load_dwordx4 v[6:9], v153, s[42:43]
	global_load_dwordx4 v[10:13], v157, s[42:43]
	s_add_u32 s42, s42, 2048
	s_addc_u32 s43, s43, 0
	s_nop 11
	global_load_dwordx4 v[144:147], v150, s[10:11]
	s_add_u32 s34, s34, 196608
	s_addc_u32 s35, s35, 0
	s_add_u32 s10, s10, 196608
	s_addc_u32 s11, s11, 0
	v_permlane32_swap_b32_e32 v16, v48
	v_permlane32_swap_b32_e32 v17, v49
	v_permlane32_swap_b32_e32 v18, v50
	v_permlane32_swap_b32_e32 v19, v51
	v_permlane32_swap_b32_e32 v20, v52
	v_permlane32_swap_b32_e32 v21, v53
	v_permlane32_swap_b32_e32 v22, v54
	v_permlane32_swap_b32_e32 v23, v55
	v_permlane32_swap_b32_e32 v24, v56
	v_permlane32_swap_b32_e32 v25, v57
	v_permlane32_swap_b32_e32 v26, v58
	v_permlane32_swap_b32_e32 v27, v59
	v_permlane32_swap_b32_e32 v28, v60
	v_permlane32_swap_b32_e32 v29, v61
	v_permlane32_swap_b32_e32 v30, v62
	v_permlane32_swap_b32_e32 v31, v63
	v_permlane32_swap_b32_e32 v32, v64
	v_permlane32_swap_b32_e32 v33, v65
	v_permlane32_swap_b32_e32 v34, v66
	v_permlane32_swap_b32_e32 v35, v67
	v_permlane32_swap_b32_e32 v36, v68
	v_permlane32_swap_b32_e32 v37, v69
	v_permlane32_swap_b32_e32 v38, v70
	v_permlane32_swap_b32_e32 v39, v71
	v_permlane32_swap_b32_e32 v40, v72
	v_permlane32_swap_b32_e32 v41, v73
	v_permlane32_swap_b32_e32 v42, v74
	v_permlane32_swap_b32_e32 v43, v75
	v_permlane32_swap_b32_e32 v44, v76
	v_permlane32_swap_b32_e32 v45, v77
	v_permlane32_swap_b32_e32 v46, v78
	v_permlane32_swap_b32_e32 v47, v79
	v_fmac_f32_e32 v16, v116, v120
	v_fmac_f32_e32 v32, v118, v121
	v_fmac_f32_dpp v16, v120, v122 quad_perm:[1,0,3,2] row_mask:0xf bank_mask:0xf
	v_fmac_f32_dpp v32, v121, v123 quad_perm:[1,0,3,2] row_mask:0xf bank_mask:0xf
	v_cvt_pk_bf16_f32 v148, v16, v32
	ds_write_b32 v151, v148
	v_fmac_f32_e32 v17, v116, v16
	v_fmac_f32_e32 v33, v118, v32
	v_fmac_f32_dpp v17, v16, v122 quad_perm:[1,0,3,2] row_mask:0xf bank_mask:0xf
	v_fmac_f32_dpp v33, v32, v123 quad_perm:[1,0,3,2] row_mask:0xf bank_mask:0xf
	v_cvt_pk_bf16_f32 v149, v17, v33
	ds_write_b32 v151, v149 offset:272
	v_fmac_f32_e32 v18, v116, v17
	v_fmac_f32_e32 v34, v118, v33
	v_fmac_f32_dpp v18, v17, v122 quad_perm:[1,0,3,2] row_mask:0xf bank_mask:0xf
	v_fmac_f32_dpp v34, v33, v123 quad_perm:[1,0,3,2] row_mask:0xf bank_mask:0xf
	v_cvt_pk_bf16_f32 v148, v18, v34
	ds_write_b32 v151, v148 offset:544
	v_fmac_f32_e32 v19, v116, v18
	v_fmac_f32_e32 v35, v118, v34
	v_fmac_f32_dpp v19, v18, v122 quad_perm:[1,0,3,2] row_mask:0xf bank_mask:0xf
	v_fmac_f32_dpp v35, v34, v123 quad_perm:[1,0,3,2] row_mask:0xf bank_mask:0xf
	v_cvt_pk_bf16_f32 v149, v19, v35
	ds_write_b32 v151, v149 offset:816
	v_fmac_f32_e32 v48, v116, v19
	v_fmac_f32_e32 v64, v118, v35
	v_fmac_f32_dpp v48, v19, v122 quad_perm:[1,0,3,2] row_mask:0xf bank_mask:0xf
	v_fmac_f32_dpp v64, v35, v123 quad_perm:[1,0,3,2] row_mask:0xf bank_mask:0xf
	v_cvt_pk_bf16_f32 v148, v48, v64
	ds_write_b32 v151, v148 offset:1088
	v_fmac_f32_e32 v49, v116, v48
	v_fmac_f32_e32 v65, v118, v64
	v_fmac_f32_dpp v49, v48, v122 quad_perm:[1,0,3,2] row_mask:0xf bank_mask:0xf
	v_fmac_f32_dpp v65, v64, v123 quad_perm:[1,0,3,2] row_mask:0xf bank_mask:0xf
	v_cvt_pk_bf16_f32 v149, v49, v65
	ds_write_b32 v151, v149 offset:1360
	v_fmac_f32_e32 v50, v116, v49
	v_fmac_f32_e32 v66, v118, v65
	v_fmac_f32_dpp v50, v49, v122 quad_perm:[1,0,3,2] row_mask:0xf bank_mask:0xf
	v_fmac_f32_dpp v66, v65, v123 quad_perm:[1,0,3,2] row_mask:0xf bank_mask:0xf
	v_cvt_pk_bf16_f32 v148, v50, v66
	ds_write_b32 v151, v148 offset:1632
	v_fmac_f32_e32 v51, v116, v50
	v_fmac_f32_e32 v67, v118, v66
	v_fmac_f32_dpp v51, v50, v122 quad_perm:[1,0,3,2] row_mask:0xf bank_mask:0xf
	v_fmac_f32_dpp v67, v66, v123 quad_perm:[1,0,3,2] row_mask:0xf bank_mask:0xf
	v_cvt_pk_bf16_f32 v149, v51, v67
	ds_write_b32 v151, v149 offset:1904
	v_fmac_f32_e32 v20, v116, v51
	v_fmac_f32_e32 v36, v118, v67
	v_fmac_f32_dpp v20, v51, v122 quad_perm:[1,0,3,2] row_mask:0xf bank_mask:0xf
	v_fmac_f32_dpp v36, v67, v123 quad_perm:[1,0,3,2] row_mask:0xf bank_mask:0xf
	v_cvt_pk_bf16_f32 v148, v20, v36
	ds_write_b32 v151, v148 offset:2176
	v_fmac_f32_e32 v21, v116, v20
	v_fmac_f32_e32 v37, v118, v36
	v_fmac_f32_dpp v21, v20, v122 quad_perm:[1,0,3,2] row_mask:0xf bank_mask:0xf
	v_fmac_f32_dpp v37, v36, v123 quad_perm:[1,0,3,2] row_mask:0xf bank_mask:0xf
	v_cvt_pk_bf16_f32 v149, v21, v37
	ds_write_b32 v151, v149 offset:2448
	v_fmac_f32_e32 v22, v116, v21
	v_fmac_f32_e32 v38, v118, v37
	v_fmac_f32_dpp v22, v21, v122 quad_perm:[1,0,3,2] row_mask:0xf bank_mask:0xf
	v_fmac_f32_dpp v38, v37, v123 quad_perm:[1,0,3,2] row_mask:0xf bank_mask:0xf
	v_cvt_pk_bf16_f32 v148, v22, v38
	ds_write_b32 v151, v148 offset:2720
	v_fmac_f32_e32 v23, v116, v22
	v_fmac_f32_e32 v39, v118, v38
	v_fmac_f32_dpp v23, v22, v122 quad_perm:[1,0,3,2] row_mask:0xf bank_mask:0xf
	v_fmac_f32_dpp v39, v38, v123 quad_perm:[1,0,3,2] row_mask:0xf bank_mask:0xf
	v_cvt_pk_bf16_f32 v149, v23, v39
	ds_write_b32 v151, v149 offset:2992
	v_fmac_f32_e32 v52, v116, v23
	v_fmac_f32_e32 v68, v118, v39
	v_fmac_f32_dpp v52, v23, v122 quad_perm:[1,0,3,2] row_mask:0xf bank_mask:0xf
	v_fmac_f32_dpp v68, v39, v123 quad_perm:[1,0,3,2] row_mask:0xf bank_mask:0xf
	v_cvt_pk_bf16_f32 v148, v52, v68
	ds_write_b32 v151, v148 offset:3264
	v_fmac_f32_e32 v53, v116, v52
	v_fmac_f32_e32 v69, v118, v68
	v_fmac_f32_dpp v53, v52, v122 quad_perm:[1,0,3,2] row_mask:0xf bank_mask:0xf
	v_fmac_f32_dpp v69, v68, v123 quad_perm:[1,0,3,2] row_mask:0xf bank_mask:0xf
	v_cvt_pk_bf16_f32 v149, v53, v69
	ds_write_b32 v151, v149 offset:3536
	v_fmac_f32_e32 v54, v116, v53
	v_fmac_f32_e32 v70, v118, v69
	v_fmac_f32_dpp v54, v53, v122 quad_perm:[1,0,3,2] row_mask:0xf bank_mask:0xf
	v_fmac_f32_dpp v70, v69, v123 quad_perm:[1,0,3,2] row_mask:0xf bank_mask:0xf
	v_cvt_pk_bf16_f32 v148, v54, v70
	ds_write_b32 v151, v148 offset:3808
	v_fmac_f32_e32 v55, v116, v54
	v_fmac_f32_e32 v71, v118, v70
	v_fmac_f32_dpp v55, v54, v122 quad_perm:[1,0,3,2] row_mask:0xf bank_mask:0xf
	v_fmac_f32_dpp v71, v70, v123 quad_perm:[1,0,3,2] row_mask:0xf bank_mask:0xf
	v_cvt_pk_bf16_f32 v149, v55, v71
	ds_write_b32 v151, v149 offset:4080
	v_fmac_f32_e32 v24, v116, v55
	v_fmac_f32_e32 v40, v118, v71
	v_fmac_f32_dpp v24, v55, v122 quad_perm:[1,0,3,2] row_mask:0xf bank_mask:0xf
	v_fmac_f32_dpp v40, v71, v123 quad_perm:[1,0,3,2] row_mask:0xf bank_mask:0xf
	v_cvt_pk_bf16_f32 v148, v24, v40
	ds_write_b32 v151, v148 offset:4352
	v_fmac_f32_e32 v25, v116, v24
	v_fmac_f32_e32 v41, v118, v40
	v_fmac_f32_dpp v25, v24, v122 quad_perm:[1,0,3,2] row_mask:0xf bank_mask:0xf
	v_fmac_f32_dpp v41, v40, v123 quad_perm:[1,0,3,2] row_mask:0xf bank_mask:0xf
	v_cvt_pk_bf16_f32 v149, v25, v41
	ds_write_b32 v151, v149 offset:4624
	v_fmac_f32_e32 v26, v116, v25
	v_fmac_f32_e32 v42, v118, v41
	v_fmac_f32_dpp v26, v25, v122 quad_perm:[1,0,3,2] row_mask:0xf bank_mask:0xf
	v_fmac_f32_dpp v42, v41, v123 quad_perm:[1,0,3,2] row_mask:0xf bank_mask:0xf
	v_cvt_pk_bf16_f32 v148, v26, v42
	ds_write_b32 v151, v148 offset:4896
	v_fmac_f32_e32 v27, v116, v26
	v_fmac_f32_e32 v43, v118, v42
	v_fmac_f32_dpp v27, v26, v122 quad_perm:[1,0,3,2] row_mask:0xf bank_mask:0xf
	v_fmac_f32_dpp v43, v42, v123 quad_perm:[1,0,3,2] row_mask:0xf bank_mask:0xf
	v_cvt_pk_bf16_f32 v149, v27, v43
	ds_write_b32 v151, v149 offset:5168
	v_fmac_f32_e32 v56, v116, v27
	v_fmac_f32_e32 v72, v118, v43
	v_fmac_f32_dpp v56, v27, v122 quad_perm:[1,0,3,2] row_mask:0xf bank_mask:0xf
	v_fmac_f32_dpp v72, v43, v123 quad_perm:[1,0,3,2] row_mask:0xf bank_mask:0xf
	v_cvt_pk_bf16_f32 v148, v56, v72
	ds_write_b32 v151, v148 offset:5440
	v_fmac_f32_e32 v57, v116, v56
	v_fmac_f32_e32 v73, v118, v72
	v_fmac_f32_dpp v57, v56, v122 quad_perm:[1,0,3,2] row_mask:0xf bank_mask:0xf
	v_fmac_f32_dpp v73, v72, v123 quad_perm:[1,0,3,2] row_mask:0xf bank_mask:0xf
	v_cvt_pk_bf16_f32 v149, v57, v73
	ds_write_b32 v151, v149 offset:5712
	v_fmac_f32_e32 v58, v116, v57
	v_fmac_f32_e32 v74, v118, v73
	v_fmac_f32_dpp v58, v57, v122 quad_perm:[1,0,3,2] row_mask:0xf bank_mask:0xf
	v_fmac_f32_dpp v74, v73, v123 quad_perm:[1,0,3,2] row_mask:0xf bank_mask:0xf
	v_cvt_pk_bf16_f32 v148, v58, v74
	ds_write_b32 v151, v148 offset:5984
	v_fmac_f32_e32 v59, v116, v58
	v_fmac_f32_e32 v75, v118, v74
	v_fmac_f32_dpp v59, v58, v122 quad_perm:[1,0,3,2] row_mask:0xf bank_mask:0xf
	v_fmac_f32_dpp v75, v74, v123 quad_perm:[1,0,3,2] row_mask:0xf bank_mask:0xf
	v_cvt_pk_bf16_f32 v149, v59, v75
	ds_write_b32 v151, v149 offset:6256
	v_fmac_f32_e32 v28, v116, v59
	v_fmac_f32_e32 v44, v118, v75
	v_fmac_f32_dpp v28, v59, v122 quad_perm:[1,0,3,2] row_mask:0xf bank_mask:0xf
	v_fmac_f32_dpp v44, v75, v123 quad_perm:[1,0,3,2] row_mask:0xf bank_mask:0xf
	v_cvt_pk_bf16_f32 v148, v28, v44
	ds_write_b32 v151, v148 offset:6528
	v_fmac_f32_e32 v29, v116, v28
	v_fmac_f32_e32 v45, v118, v44
	v_fmac_f32_dpp v29, v28, v122 quad_perm:[1,0,3,2] row_mask:0xf bank_mask:0xf
	v_fmac_f32_dpp v45, v44, v123 quad_perm:[1,0,3,2] row_mask:0xf bank_mask:0xf
	v_cvt_pk_bf16_f32 v149, v29, v45
	ds_write_b32 v151, v149 offset:6800
	v_fmac_f32_e32 v30, v116, v29
	v_fmac_f32_e32 v46, v118, v45
	v_fmac_f32_dpp v30, v29, v122 quad_perm:[1,0,3,2] row_mask:0xf bank_mask:0xf
	v_fmac_f32_dpp v46, v45, v123 quad_perm:[1,0,3,2] row_mask:0xf bank_mask:0xf
	v_cvt_pk_bf16_f32 v148, v30, v46
	ds_write_b32 v151, v148 offset:7072
	v_fmac_f32_e32 v31, v116, v30
	v_fmac_f32_e32 v47, v118, v46
	v_fmac_f32_dpp v31, v30, v122 quad_perm:[1,0,3,2] row_mask:0xf bank_mask:0xf
	v_fmac_f32_dpp v47, v46, v123 quad_perm:[1,0,3,2] row_mask:0xf bank_mask:0xf
	v_cvt_pk_bf16_f32 v149, v31, v47
	ds_write_b32 v151, v149 offset:7344
	v_fmac_f32_e32 v60, v116, v31
	v_fmac_f32_e32 v76, v118, v47
	v_fmac_f32_dpp v60, v31, v122 quad_perm:[1,0,3,2] row_mask:0xf bank_mask:0xf
	v_fmac_f32_dpp v76, v47, v123 quad_perm:[1,0,3,2] row_mask:0xf bank_mask:0xf
	v_cvt_pk_bf16_f32 v148, v60, v76
	ds_write_b32 v151, v148 offset:7616
	v_fmac_f32_e32 v61, v116, v60
	v_fmac_f32_e32 v77, v118, v76
	v_fmac_f32_dpp v61, v60, v122 quad_perm:[1,0,3,2] row_mask:0xf bank_mask:0xf
	v_fmac_f32_dpp v77, v76, v123 quad_perm:[1,0,3,2] row_mask:0xf bank_mask:0xf
	v_cvt_pk_bf16_f32 v149, v61, v77
	ds_write_b32 v151, v149 offset:7888
	v_fmac_f32_e32 v62, v116, v61
	v_fmac_f32_e32 v78, v118, v77
	v_fmac_f32_dpp v62, v61, v122 quad_perm:[1,0,3,2] row_mask:0xf bank_mask:0xf
	v_fmac_f32_dpp v78, v77, v123 quad_perm:[1,0,3,2] row_mask:0xf bank_mask:0xf
	v_cvt_pk_bf16_f32 v148, v62, v78
	ds_write_b32 v151, v148 offset:8160
	v_fmac_f32_e32 v63, v116, v62
	v_fmac_f32_e32 v79, v118, v78
	v_fmac_f32_dpp v63, v62, v122 quad_perm:[1,0,3,2] row_mask:0xf bank_mask:0xf
	v_fmac_f32_dpp v79, v78, v123 quad_perm:[1,0,3,2] row_mask:0xf bank_mask:0xf
	v_cvt_pk_bf16_f32 v149, v63, v79
	ds_write_b32 v151, v149 offset:8432
	v_mov_b32_e32 v120, v63
	v_mov_b32_e32 v121, v79
	ds_read_b128 v[124:127], v152
	ds_read_b128 v[128:131], v152 offset:64
	ds_read_b128 v[132:135], v152 offset:128
	ds_read_b128 v[136:139], v152 offset:192
	ds_read_b64 v[160:161], v163
	s_waitcnt lgkmcnt(4)
	v_mfma_f32_16x16x32_bf16 v[140:143], v[100:103], v[124:127], 0
	s_waitcnt lgkmcnt(3)
	v_mfma_f32_16x16x32_bf16 v[140:143], v[104:107], v[128:131], v[140:143]
	s_waitcnt lgkmcnt(2)
	v_mfma_f32_16x16x32_bf16 v[140:143], v[108:111], v[132:135], v[140:143]
	s_waitcnt lgkmcnt(1)
	v_mfma_f32_16x16x32_bf16 v[140:143], v[112:115], v[136:139], v[140:143]
	s_nop 9
	s_waitcnt vmcnt(7) lgkmcnt(0)
	v_add_f32_e32 v182, v172, v140
	v_add_f32_e32 v183, v173, v141
	v_add_f32_e32 v184, v174, v142
	v_add_f32_e32 v185, v175, v143
	v_lshlrev_b32_e32 v186, 16, v160
	v_and_b32_e32 v187, 0xffff0000, v160
	v_lshlrev_b32_e32 v188, 16, v161
	v_and_b32_e32 v189, 0xffff0000, v161
	v_fmac_f32_e32 v182, v164, v186
	v_fmac_f32_e32 v183, v165, v187
	v_fmac_f32_e32 v184, v166, v188
	v_fmac_f32_e32 v185, v167, v189
	v_mul_f32_e32 v186, 0x3d372713, v182
	v_mul_f32_e32 v187, 0x3d372713, v183
	v_mul_f32_e32 v188, 0x3d372713, v184
	v_mul_f32_e32 v189, 0x3d372713, v185
	v_mul_f32_e32 v186, v182, v186
	v_mul_f32_e32 v187, v183, v187
	v_mul_f32_e32 v188, v184, v188
	v_mul_f32_e32 v189, v185, v189
	v_fma_f32 v186, v182, v186, v182
	v_fma_f32 v187, v183, v187, v183
	v_fma_f32 v188, v184, v188, v184
	v_fma_f32 v189, v185, v189, v185
	v_mul_f32_e32 v186, 0xbfcc422a, v186
	v_mul_f32_e32 v187, 0xbfcc422a, v187
	v_mul_f32_e32 v188, 0xbfcc422a, v188
	v_mul_f32_e32 v189, 0xbfcc422a, v189
	v_mul_f32_e32 v186, 0x3fb8aa3b, v186
	v_mul_f32_e32 v187, 0x3fb8aa3b, v187
	v_mul_f32_e32 v188, 0x3fb8aa3b, v188
	v_mul_f32_e32 v189, 0x3fb8aa3b, v189
	v_exp_f32_e32 v186, v186
	v_exp_f32_e32 v187, v187
	v_exp_f32_e32 v188, v188
	v_exp_f32_e32 v189, v189
	v_add_f32_e32 v186, 1.0, v186
	v_add_f32_e32 v187, 1.0, v187
	v_add_f32_e32 v188, 1.0, v188
	v_add_f32_e32 v189, 1.0, v189
	v_rcp_f32_e32 v186, v186
	v_rcp_f32_e32 v187, v187
	v_rcp_f32_e32 v188, v188
	v_rcp_f32_e32 v189, v189
	v_mul_f32_e32 v182, v182, v186
	v_mul_f32_e32 v183, v183, v187
	v_mul_f32_e32 v184, v184, v188
	v_mul_f32_e32 v185, v185, v189
	v_cvt_pk_bf16_f32 v148, v182, v183
	v_cvt_pk_bf16_f32 v149, v184, v185
	global_store_dwordx2 v156, v[148:149], s[12:13]
	ds_read_b128 v[124:127], v152 offset:4352
	ds_read_b128 v[128:131], v152 offset:4416
	ds_read_b128 v[132:135], v152 offset:4480
	ds_read_b128 v[136:139], v152 offset:4544
	ds_read_b64 v[160:161], v163 offset:512
	s_waitcnt lgkmcnt(4)
	v_mfma_f32_16x16x32_bf16 v[140:143], v[100:103], v[124:127], 0
	s_waitcnt lgkmcnt(3)
	v_mfma_f32_16x16x32_bf16 v[140:143], v[104:107], v[128:131], v[140:143]
	s_waitcnt lgkmcnt(2)
	v_mfma_f32_16x16x32_bf16 v[140:143], v[108:111], v[132:135], v[140:143]
	s_waitcnt lgkmcnt(1)
	v_mfma_f32_16x16x32_bf16 v[140:143], v[112:115], v[136:139], v[140:143]
	s_nop 9
	s_waitcnt vmcnt(7) lgkmcnt(0)
	v_add_f32_e32 v182, v176, v140
	v_add_f32_e32 v183, v177, v141
	v_add_f32_e32 v184, v178, v142
	v_add_f32_e32 v185, v179, v143
	v_lshlrev_b32_e32 v186, 16, v160
	v_and_b32_e32 v187, 0xffff0000, v160
	v_lshlrev_b32_e32 v188, 16, v161
	v_and_b32_e32 v189, 0xffff0000, v161
	v_fmac_f32_e32 v182, v164, v186
	v_fmac_f32_e32 v183, v165, v187
	v_fmac_f32_e32 v184, v166, v188
	v_fmac_f32_e32 v185, v167, v189
	v_mul_f32_e32 v186, 0x3d372713, v182
	v_mul_f32_e32 v187, 0x3d372713, v183
	v_mul_f32_e32 v188, 0x3d372713, v184
	v_mul_f32_e32 v189, 0x3d372713, v185
	v_mul_f32_e32 v186, v182, v186
	v_mul_f32_e32 v187, v183, v187
	v_mul_f32_e32 v188, v184, v188
	v_mul_f32_e32 v189, v185, v189
	v_fma_f32 v186, v182, v186, v182
	v_fma_f32 v187, v183, v187, v183
	v_fma_f32 v188, v184, v188, v184
	v_fma_f32 v189, v185, v189, v185
	v_mul_f32_e32 v186, 0xbfcc422a, v186
	v_mul_f32_e32 v187, 0xbfcc422a, v187
	v_mul_f32_e32 v188, 0xbfcc422a, v188
	v_mul_f32_e32 v189, 0xbfcc422a, v189
	v_mul_f32_e32 v186, 0x3fb8aa3b, v186
	v_mul_f32_e32 v187, 0x3fb8aa3b, v187
	v_mul_f32_e32 v188, 0x3fb8aa3b, v188
	v_mul_f32_e32 v189, 0x3fb8aa3b, v189
	v_exp_f32_e32 v186, v186
	v_exp_f32_e32 v187, v187
	v_exp_f32_e32 v188, v188
	v_exp_f32_e32 v189, v189
	v_add_f32_e32 v186, 1.0, v186
	v_add_f32_e32 v187, 1.0, v187
	v_add_f32_e32 v188, 1.0, v188
	v_add_f32_e32 v189, 1.0, v189
	v_rcp_f32_e32 v186, v186
	v_rcp_f32_e32 v187, v187
	v_rcp_f32_e32 v188, v188
	v_rcp_f32_e32 v189, v189
	v_mul_f32_e32 v182, v182, v186
	v_mul_f32_e32 v183, v183, v187
	v_mul_f32_e32 v184, v184, v188
	v_mul_f32_e32 v185, v185, v189
	v_cvt_pk_bf16_f32 v148, v182, v183
	v_cvt_pk_bf16_f32 v149, v184, v185
	global_store_dwordx2 v159, v[148:149], s[12:13]
	s_add_u32 s12, s12, 65536
	s_addc_u32 s13, s13, 0
	s_add_u32 s14, s14, 2
	s_cmp_lt_u32 s14, 32
	s_cbranch_scc1 .Lssm_tileB_d0m0
	s_waitcnt vmcnt(0) lgkmcnt(0)
	s_branch .Lssm_lat_join
.Lssm_lat_bwd:
	s_add_u32 s28, s24, 64
	s_lshl_b32 s29, s28, 13
	s_add_u32 s29, s29, 0x200000
	s_add_u32 s10, s62, s29
	s_addc_u32 s11, s63, 0
	global_load_dwordx4 v[84:87], v177, s[10:11]
	global_load_dwordx4 v[88:91], v177, s[10:11] offset:2048
	s_add_u32 s12, s10, 0x1000
	s_addc_u32 s13, s11, 0
	global_load_dwordx4 v[92:95], v177, s[12:13]
	global_load_dwordx4 v[96:99], v177, s[12:13] offset:2048
	s_lshl_b32 s29, s28, 12
	s_add_u32 s29, s29, 0x300000
	s_add_u32 s16, s62, s29
	s_addc_u32 s17, s63, 0
	global_load_dwordx2 v[2:3], v178, s[16:17]
	global_load_dwordx2 v[4:5], v178, s[16:17] offset:1024
	global_load_dwordx2 v[6:7], v178, s[16:17] offset:512
	global_load_dwordx2 v[8:9], v178, s[16:17] offset:1536
	global_load_dwordx2 v[10:11], v178, s[16:17] offset:2048
	global_load_dwordx2 v[12:13], v178, s[16:17] offset:3072
	global_load_dwordx2 v[14:15], v178, s[16:17] offset:2560
	global_load_dwordx2 v[16:17], v178, s[16:17] offset:3584
	s_lshl_b32 s29, s28, 9
	s_add_u32 s29, s29, 0x100000
	s_add_u32 s18, s62, s29
	s_addc_u32 s19, s63, 0
	global_load_dwordx2 v[116:117], v179, s[18:19]
	global_load_dwordx2 v[118:119], v179, s[18:19] offset:128
	s_lshl_b32 s30, s23, 1
	s_add_u32 s30, s30, 1
	s_lshl_b32 s30, s30, 15
	s_lshl_b32 s31, s24, 8
	s_add_u32 s30, s30, s31
	v_readlane_b32 s34, v254, 10
	v_readlane_b32 s35, v254, 11
	s_nop 3
	s_add_u32 s34, s34, s30
	s_addc_u32 s35, s35, 0
	global_load_dword v120, v180, s[34:35]
	global_load_dword v121, v180, s[34:35] offset:64
	v_readlane_b32 s34, v254, 28
	v_readlane_b32 s35, v254, 29
	s_nop 3
	s_lshl_b32 s31, s24, 6
	s_add_u32 s34, s34, s31
	s_addc_u32 s35, s35, 0
	global_load_dwordx4 v[164:167], v181, s[34:35]
	s_mul_i32 s31, s25, 0x1800
	s_lshl_b32 s29, s24, 5
	s_add_u32 s31, s31, s29
	s_add_u32 s31, s31, 0x8801000
	s_add_u32 s4, s62, s31
	s_addc_u32 s5, s63, 0
	s_lshl_b32 s31, s22, 1
	s_add_u32 s31, s31, 1
	s_lshl_b32 s31, s31, 15
	s_add_u32 s31, s31, 0x4800000
	s_add_u32 s6, s62, s31
	s_addc_u32 s7, s63, 0
	s_add_u32 s34, s4, 6094848
	s_addc_u32 s35, s5, 0
	global_load_dwordx4 v[80:83], v150, s[34:35]
	s_mov_b64 s[10:11], s[34:35]
	s_sub_u32 s10, s10, 196608
	s_subb_u32 s11, s11, 0
	global_load_dwordx4 v[144:147], v150, s[10:11]
	s_mov_b64 s[34:35], s[10:11]
	s_sub_u32 s10, s10, 196608
	s_subb_u32 s11, s11, 0
	s_add_u32 s12, s6, 30720
	s_addc_u32 s13, s7, 0
	s_mov_b32 s14, 0
	s_mov_b32 s40, 0xffff0000
	s_waitcnt vmcnt(0)
	v_and_b32_e32 v182, 0xffff, v2
	v_lshrrev_b32_e32 v183, 16, v2
	v_and_b32_e32 v184, 0xffff, v3
	v_lshrrev_b32_e32 v185, 16, v3
	v_lshl_or_b32 v100, v4, 16, v182
	v_and_or_b32 v101, v4, s40, v183
	v_lshl_or_b32 v102, v5, 16, v184
	v_and_or_b32 v103, v5, s40, v185
	v_and_b32_e32 v182, 0xffff, v6
	v_lshrrev_b32_e32 v183, 16, v6
	v_and_b32_e32 v184, 0xffff, v7
	v_lshrrev_b32_e32 v185, 16, v7
	v_lshl_or_b32 v104, v8, 16, v182
	v_and_or_b32 v105, v8, s40, v183
	v_lshl_or_b32 v106, v9, 16, v184
	v_and_or_b32 v107, v9, s40, v185
	v_and_b32_e32 v182, 0xffff, v10
	v_lshrrev_b32_e32 v183, 16, v10
	v_and_b32_e32 v184, 0xffff, v11
	v_lshrrev_b32_e32 v185, 16, v11
	v_lshl_or_b32 v108, v12, 16, v182
	v_and_or_b32 v109, v12, s40, v183
	v_lshl_or_b32 v110, v13, 16, v184
	v_and_or_b32 v111, v13, s40, v185
	v_and_b32_e32 v182, 0xffff, v14
	v_lshrrev_b32_e32 v183, 16, v14
	v_and_b32_e32 v184, 0xffff, v15
	v_lshrrev_b32_e32 v185, 16, v15
	v_lshl_or_b32 v112, v16, 16, v182
	v_and_or_b32 v113, v16, s40, v183
	v_lshl_or_b32 v114, v17, 16, v184
	v_and_or_b32 v115, v17, s40, v185
	v_cmp_eq_u32_e32 vcc, 1, v174
	v_xor_b32_e32 v182, 0x80000000, v117
	v_xor_b32_e32 v183, 0x80000000, v119
	s_nop 1
	v_cndmask_b32_e32 v122, v182, v117, vcc
	v_cndmask_b32_e32 v123, v183, v119, vcc
.Lssm_tileA_d1m0:
	s_waitcnt vmcnt(5)
	v_mfma_f32_32x32x16_bf16 v[16:31], v[80:83], v[84:87], 0
	v_mfma_f32_32x32x16_bf16 v[32:47], v[80:83], v[88:91], 0
	v_mfma_f32_32x32x16_bf16 v[48:63], v[80:83], v[92:95], 0
	v_mfma_f32_32x32x16_bf16 v[64:79], v[80:83], v[96:99], 0
	s_nop 11
	global_load_dwordx4 v[80:83], v150, s[10:11]
	s_sub_u32 s34, s34, 196608
	s_subb_u32 s35, s35, 0
	s_sub_u32 s10, s10, 196608
	s_subb_u32 s11, s11, 0
	v_permlane32_swap_b32_e32 v16, v48
	v_permlane32_swap_b32_e32 v17, v49
	v_permlane32_swap_b32_e32 v18, v50
	v_permlane32_swap_b32_e32 v19, v51
	v_permlane32_swap_b32_e32 v20, v52
	v_permlane32_swap_b32_e32 v21, v53
	v_permlane32_swap_b32_e32 v22, v54
	v_permlane32_swap_b32_e32 v23, v55
	v_permlane32_swap_b32_e32 v24, v56
	v_permlane32_swap_b32_e32 v25, v57
	v_permlane32_swap_b32_e32 v26, v58
	v_permlane32_swap_b32_e32 v27, v59
	v_permlane32_swap_b32_e32 v28, v60
	v_permlane32_swap_b32_e32 v29, v61
	v_permlane32_swap_b32_e32 v30, v62
	v_permlane32_swap_b32_e32 v31, v63
	v_permlane32_swap_b32_e32 v32, v64
	v_permlane32_swap_b32_e32 v33, v65
	v_permlane32_swap_b32_e32 v34, v66
	v_permlane32_swap_b32_e32 v35, v67
	v_permlane32_swap_b32_e32 v36, v68
	v_permlane32_swap_b32_e32 v37, v69
	v_permlane32_swap_b32_e32 v38, v70
	v_permlane32_swap_b32_e32 v39, v71
	v_permlane32_swap_b32_e32 v40, v72
	v_permlane32_swap_b32_e32 v41, v73
	v_permlane32_swap_b32_e32 v42, v74
	v_permlane32_swap_b32_e32 v43, v75
	v_permlane32_swap_b32_e32 v44, v76
	v_permlane32_swap_b32_e32 v45, v77
	v_permlane32_swap_b32_e32 v46, v78
	v_permlane32_swap_b32_e32 v47, v79
	v_fmac_f32_e32 v63, v116, v120
	v_fmac_f32_e32 v79, v118, v121
	v_fmac_f32_dpp v63, v120, v122 quad_perm:[1,0,3,2] row_mask:0xf bank_mask:0xf
	v_fmac_f32_dpp v79, v121, v123 quad_perm:[1,0,3,2] row_mask:0xf bank_mask:0xf
	v_cvt_pk_bf16_f32 v148, v63, v79
	ds_write_b32 v151, v148 offset:8432
	v_fmac_f32_e32 v62, v116, v63
	v_fmac_f32_e32 v78, v118, v79
	v_fmac_f32_dpp v62, v63, v122 quad_perm:[1,0,3,2] row_mask:0xf bank_mask:0xf
	v_fmac_f32_dpp v78, v79, v123 quad_perm:[1,0,3,2] row_mask:0xf bank_mask:0xf
	v_cvt_pk_bf16_f32 v149, v62, v78
	ds_write_b32 v151, v149 offset:8160
	v_fmac_f32_e32 v61, v116, v62
	v_fmac_f32_e32 v77, v118, v78
	v_fmac_f32_dpp v61, v62, v122 quad_perm:[1,0,3,2] row_mask:0xf bank_mask:0xf
	v_fmac_f32_dpp v77, v78, v123 quad_perm:[1,0,3,2] row_mask:0xf bank_mask:0xf
	v_cvt_pk_bf16_f32 v148, v61, v77
	ds_write_b32 v151, v148 offset:7888
	v_fmac_f32_e32 v60, v116, v61
	v_fmac_f32_e32 v76, v118, v77
	v_fmac_f32_dpp v60, v61, v122 quad_perm:[1,0,3,2] row_mask:0xf bank_mask:0xf
	v_fmac_f32_dpp v76, v77, v123 quad_perm:[1,0,3,2] row_mask:0xf bank_mask:0xf
	v_cvt_pk_bf16_f32 v149, v60, v76
	ds_write_b32 v151, v149 offset:7616
	v_fmac_f32_e32 v31, v116, v60
	v_fmac_f32_e32 v47, v118, v76
	v_fmac_f32_dpp v31, v60, v122 quad_perm:[1,0,3,2] row_mask:0xf bank_mask:0xf
	v_fmac_f32_dpp v47, v76, v123 quad_perm:[1,0,3,2] row_mask:0xf bank_mask:0xf
	v_cvt_pk_bf16_f32 v148, v31, v47
	ds_write_b32 v151, v148 offset:7344
	v_fmac_f32_e32 v30, v116, v31
	v_fmac_f32_e32 v46, v118, v47
	v_fmac_f32_dpp v30, v31, v122 quad_perm:[1,0,3,2] row_mask:0xf bank_mask:0xf
	v_fmac_f32_dpp v46, v47, v123 quad_perm:[1,0,3,2] row_mask:0xf bank_mask:0xf
	v_cvt_pk_bf16_f32 v149, v30, v46
	ds_write_b32 v151, v149 offset:7072
	v_fmac_f32_e32 v29, v116, v30
	v_fmac_f32_e32 v45, v118, v46
	v_fmac_f32_dpp v29, v30, v122 quad_perm:[1,0,3,2] row_mask:0xf bank_mask:0xf
	v_fmac_f32_dpp v45, v46, v123 quad_perm:[1,0,3,2] row_mask:0xf bank_mask:0xf
	v_cvt_pk_bf16_f32 v148, v29, v45
	ds_write_b32 v151, v148 offset:6800
	v_fmac_f32_e32 v28, v116, v29
	v_fmac_f32_e32 v44, v118, v45
	v_fmac_f32_dpp v28, v29, v122 quad_perm:[1,0,3,2] row_mask:0xf bank_mask:0xf
	v_fmac_f32_dpp v44, v45, v123 quad_perm:[1,0,3,2] row_mask:0xf bank_mask:0xf
	v_cvt_pk_bf16_f32 v149, v28, v44
	ds_write_b32 v151, v149 offset:6528
	v_fmac_f32_e32 v59, v116, v28
	v_fmac_f32_e32 v75, v118, v44
	v_fmac_f32_dpp v59, v28, v122 quad_perm:[1,0,3,2] row_mask:0xf bank_mask:0xf
	v_fmac_f32_dpp v75, v44, v123 quad_perm:[1,0,3,2] row_mask:0xf bank_mask:0xf
	v_cvt_pk_bf16_f32 v148, v59, v75
	ds_write_b32 v151, v148 offset:6256
	v_fmac_f32_e32 v58, v116, v59
	v_fmac_f32_e32 v74, v118, v75
	v_fmac_f32_dpp v58, v59, v122 quad_perm:[1,0,3,2] row_mask:0xf bank_mask:0xf
	v_fmac_f32_dpp v74, v75, v123 quad_perm:[1,0,3,2] row_mask:0xf bank_mask:0xf
	v_cvt_pk_bf16_f32 v149, v58, v74
	ds_write_b32 v151, v149 offset:5984
	v_fmac_f32_e32 v57, v116, v58
	v_fmac_f32_e32 v73, v118, v74
	v_fmac_f32_dpp v57, v58, v122 quad_perm:[1,0,3,2] row_mask:0xf bank_mask:0xf
	v_fmac_f32_dpp v73, v74, v123 quad_perm:[1,0,3,2] row_mask:0xf bank_mask:0xf
	v_cvt_pk_bf16_f32 v148, v57, v73
	ds_write_b32 v151, v148 offset:5712
	v_fmac_f32_e32 v56, v116, v57
	v_fmac_f32_e32 v72, v118, v73
	v_fmac_f32_dpp v56, v57, v122 quad_perm:[1,0,3,2] row_mask:0xf bank_mask:0xf
	v_fmac_f32_dpp v72, v73, v123 quad_perm:[1,0,3,2] row_mask:0xf bank_mask:0xf
	v_cvt_pk_bf16_f32 v149, v56, v72
	ds_write_b32 v151, v149 offset:5440
	v_fmac_f32_e32 v27, v116, v56
	v_fmac_f32_e32 v43, v118, v72
	v_fmac_f32_dpp v27, v56, v122 quad_perm:[1,0,3,2] row_mask:0xf bank_mask:0xf
	v_fmac_f32_dpp v43, v72, v123 quad_perm:[1,0,3,2] row_mask:0xf bank_mask:0xf
	v_cvt_pk_bf16_f32 v148, v27, v43
	ds_write_b32 v151, v148 offset:5168
	v_fmac_f32_e32 v26, v116, v27
	v_fmac_f32_e32 v42, v118, v43
	v_fmac_f32_dpp v26, v27, v122 quad_perm:[1,0,3,2] row_mask:0xf bank_mask:0xf
	v_fmac_f32_dpp v42, v43, v123 quad_perm:[1,0,3,2] row_mask:0xf bank_mask:0xf
	v_cvt_pk_bf16_f32 v149, v26, v42
	ds_write_b32 v151, v149 offset:4896
	v_fmac_f32_e32 v25, v116, v26
	v_fmac_f32_e32 v41, v118, v42
	v_fmac_f32_dpp v25, v26, v122 quad_perm:[1,0,3,2] row_mask:0xf bank_mask:0xf
	v_fmac_f32_dpp v41, v42, v123 quad_perm:[1,0,3,2] row_mask:0xf bank_mask:0xf
	v_cvt_pk_bf16_f32 v148, v25, v41
	ds_write_b32 v151, v148 offset:4624
	v_fmac_f32_e32 v24, v116, v25
	v_fmac_f32_e32 v40, v118, v41
	v_fmac_f32_dpp v24, v25, v122 quad_perm:[1,0,3,2] row_mask:0xf bank_mask:0xf
	v_fmac_f32_dpp v40, v41, v123 quad_perm:[1,0,3,2] row_mask:0xf bank_mask:0xf
	v_cvt_pk_bf16_f32 v149, v24, v40
	ds_write_b32 v151, v149 offset:4352
	v_fmac_f32_e32 v55, v116, v24
	v_fmac_f32_e32 v71, v118, v40
	v_fmac_f32_dpp v55, v24, v122 quad_perm:[1,0,3,2] row_mask:0xf bank_mask:0xf
	v_fmac_f32_dpp v71, v40, v123 quad_perm:[1,0,3,2] row_mask:0xf bank_mask:0xf
	v_cvt_pk_bf16_f32 v148, v55, v71
	ds_write_b32 v151, v148 offset:4080
	v_fmac_f32_e32 v54, v116, v55
	v_fmac_f32_e32 v70, v118, v71
	v_fmac_f32_dpp v54, v55, v122 quad_perm:[1,0,3,2] row_mask:0xf bank_mask:0xf
	v_fmac_f32_dpp v70, v71, v123 quad_perm:[1,0,3,2] row_mask:0xf bank_mask:0xf
	v_cvt_pk_bf16_f32 v149, v54, v70
	ds_write_b32 v151, v149 offset:3808
	v_fmac_f32_e32 v53, v116, v54
	v_fmac_f32_e32 v69, v118, v70
	v_fmac_f32_dpp v53, v54, v122 quad_perm:[1,0,3,2] row_mask:0xf bank_mask:0xf
	v_fmac_f32_dpp v69, v70, v123 quad_perm:[1,0,3,2] row_mask:0xf bank_mask:0xf
	v_cvt_pk_bf16_f32 v148, v53, v69
	ds_write_b32 v151, v148 offset:3536
	v_fmac_f32_e32 v52, v116, v53
	v_fmac_f32_e32 v68, v118, v69
	v_fmac_f32_dpp v52, v53, v122 quad_perm:[1,0,3,2] row_mask:0xf bank_mask:0xf
	v_fmac_f32_dpp v68, v69, v123 quad_perm:[1,0,3,2] row_mask:0xf bank_mask:0xf
	v_cvt_pk_bf16_f32 v149, v52, v68
	ds_write_b32 v151, v149 offset:3264
	v_fmac_f32_e32 v23, v116, v52
	v_fmac_f32_e32 v39, v118, v68
	v_fmac_f32_dpp v23, v52, v122 quad_perm:[1,0,3,2] row_mask:0xf bank_mask:0xf
	v_fmac_f32_dpp v39, v68, v123 quad_perm:[1,0,3,2] row_mask:0xf bank_mask:0xf
	v_cvt_pk_bf16_f32 v148, v23, v39
	ds_write_b32 v151, v148 offset:2992
	v_fmac_f32_e32 v22, v116, v23
	v_fmac_f32_e32 v38, v118, v39
	v_fmac_f32_dpp v22, v23, v122 quad_perm:[1,0,3,2] row_mask:0xf bank_mask:0xf
	v_fmac_f32_dpp v38, v39, v123 quad_perm:[1,0,3,2] row_mask:0xf bank_mask:0xf
	v_cvt_pk_bf16_f32 v149, v22, v38
	ds_write_b32 v151, v149 offset:2720
	v_fmac_f32_e32 v21, v116, v22
	v_fmac_f32_e32 v37, v118, v38
	v_fmac_f32_dpp v21, v22, v122 quad_perm:[1,0,3,2] row_mask:0xf bank_mask:0xf
	v_fmac_f32_dpp v37, v38, v123 quad_perm:[1,0,3,2] row_mask:0xf bank_mask:0xf
	v_cvt_pk_bf16_f32 v148, v21, v37
	ds_write_b32 v151, v148 offset:2448
	v_fmac_f32_e32 v20, v116, v21
	v_fmac_f32_e32 v36, v118, v37
	v_fmac_f32_dpp v20, v21, v122 quad_perm:[1,0,3,2] row_mask:0xf bank_mask:0xf
	v_fmac_f32_dpp v36, v37, v123 quad_perm:[1,0,3,2] row_mask:0xf bank_mask:0xf
	v_cvt_pk_bf16_f32 v149, v20, v36
	ds_write_b32 v151, v149 offset:2176
	v_fmac_f32_e32 v51, v116, v20
	v_fmac_f32_e32 v67, v118, v36
	v_fmac_f32_dpp v51, v20, v122 quad_perm:[1,0,3,2] row_mask:0xf bank_mask:0xf
	v_fmac_f32_dpp v67, v36, v123 quad_perm:[1,0,3,2] row_mask:0xf bank_mask:0xf
	v_cvt_pk_bf16_f32 v148, v51, v67
	ds_write_b32 v151, v148 offset:1904
	v_fmac_f32_e32 v50, v116, v51
	v_fmac_f32_e32 v66, v118, v67
	v_fmac_f32_dpp v50, v51, v122 quad_perm:[1,0,3,2] row_mask:0xf bank_mask:0xf
	v_fmac_f32_dpp v66, v67, v123 quad_perm:[1,0,3,2] row_mask:0xf bank_mask:0xf
	v_cvt_pk_bf16_f32 v149, v50, v66
	ds_write_b32 v151, v149 offset:1632
	v_fmac_f32_e32 v49, v116, v50
	v_fmac_f32_e32 v65, v118, v66
	v_fmac_f32_dpp v49, v50, v122 quad_perm:[1,0,3,2] row_mask:0xf bank_mask:0xf
	v_fmac_f32_dpp v65, v66, v123 quad_perm:[1,0,3,2] row_mask:0xf bank_mask:0xf
	v_cvt_pk_bf16_f32 v148, v49, v65
	ds_write_b32 v151, v148 offset:1360
	v_fmac_f32_e32 v48, v116, v49
	v_fmac_f32_e32 v64, v118, v65
	v_fmac_f32_dpp v48, v49, v122 quad_perm:[1,0,3,2] row_mask:0xf bank_mask:0xf
	v_fmac_f32_dpp v64, v65, v123 quad_perm:[1,0,3,2] row_mask:0xf bank_mask:0xf
	v_cvt_pk_bf16_f32 v149, v48, v64
	ds_write_b32 v151, v149 offset:1088
	v_fmac_f32_e32 v19, v116, v48
	v_fmac_f32_e32 v35, v118, v64
	v_fmac_f32_dpp v19, v48, v122 quad_perm:[1,0,3,2] row_mask:0xf bank_mask:0xf
	v_fmac_f32_dpp v35, v64, v123 quad_perm:[1,0,3,2] row_mask:0xf bank_mask:0xf
	v_cvt_pk_bf16_f32 v148, v19, v35
	ds_write_b32 v151, v148 offset:816
	v_fmac_f32_e32 v18, v116, v19
	v_fmac_f32_e32 v34, v118, v35
	v_fmac_f32_dpp v18, v19, v122 quad_perm:[1,0,3,2] row_mask:0xf bank_mask:0xf
	v_fmac_f32_dpp v34, v35, v123 quad_perm:[1,0,3,2] row_mask:0xf bank_mask:0xf
	v_cvt_pk_bf16_f32 v149, v18, v34
	ds_write_b32 v151, v149 offset:544
	v_fmac_f32_e32 v17, v116, v18
	v_fmac_f32_e32 v33, v118, v34
	v_fmac_f32_dpp v17, v18, v122 quad_perm:[1,0,3,2] row_mask:0xf bank_mask:0xf
	v_fmac_f32_dpp v33, v34, v123 quad_perm:[1,0,3,2] row_mask:0xf bank_mask:0xf
	v_cvt_pk_bf16_f32 v148, v17, v33
	ds_write_b32 v151, v148 offset:272
	v_fmac_f32_e32 v16, v116, v17
	v_fmac_f32_e32 v32, v118, v33
	v_fmac_f32_dpp v16, v17, v122 quad_perm:[1,0,3,2] row_mask:0xf bank_mask:0xf
	v_fmac_f32_dpp v32, v33, v123 quad_perm:[1,0,3,2] row_mask:0xf bank_mask:0xf
	v_cvt_pk_bf16_f32 v149, v16, v32
	ds_write_b32 v151, v149
	v_mov_b32_e32 v120, v16
	v_mov_b32_e32 v121, v32
	ds_read_b128 v[124:127], v152
	ds_read_b128 v[128:131], v152 offset:64
	ds_read_b128 v[132:135], v152 offset:128
	ds_read_b128 v[136:139], v152 offset:192
	s_waitcnt lgkmcnt(3)
	v_mfma_f32_16x16x32_bf16 v[140:143], v[100:103], v[124:127], 0
	s_waitcnt lgkmcnt(2)
	v_mfma_f32_16x16x32_bf16 v[140:143], v[104:107], v[128:131], v[140:143]
	s_waitcnt lgkmcnt(1)
	v_mfma_f32_16x16x32_bf16 v[140:143], v[108:111], v[132:135], v[140:143]
	s_waitcnt lgkmcnt(0)
	v_mfma_f32_16x16x32_bf16 v[140:143], v[112:115], v[136:139], v[140:143]
	s_nop 9
	global_store_dwordx4 v153, v[140:143], s[12:13]
	s_nop 1
	ds_read_b128 v[124:127], v152 offset:4352
	ds_read_b128 v[128:131], v152 offset:4416
	ds_read_b128 v[132:135], v152 offset:4480
	ds_read_b128 v[136:139], v152 offset:4544
	s_waitcnt lgkmcnt(3)
	v_mfma_f32_16x16x32_bf16 v[140:143], v[100:103], v[124:127], 0
	s_waitcnt lgkmcnt(2)
	v_mfma_f32_16x16x32_bf16 v[140:143], v[104:107], v[128:131], v[140:143]
	s_waitcnt lgkmcnt(1)
	v_mfma_f32_16x16x32_bf16 v[140:143], v[108:111], v[132:135], v[140:143]
	s_waitcnt lgkmcnt(0)
	v_mfma_f32_16x16x32_bf16 v[140:143], v[112:115], v[136:139], v[140:143]
	s_nop 9
	global_store_dwordx4 v157, v[140:143], s[12:13]
	s_nop 1
	s_sub_u32 s12, s12, 2048
	s_subb_u32 s13, s13, 0
	s_waitcnt vmcnt(5)
	v_mfma_f32_32x32x16_bf16 v[16:31], v[144:147], v[84:87], 0
	v_mfma_f32_32x32x16_bf16 v[32:47], v[144:147], v[88:91], 0
	v_mfma_f32_32x32x16_bf16 v[48:63], v[144:147], v[92:95], 0
	v_mfma_f32_32x32x16_bf16 v[64:79], v[144:147], v[96:99], 0
	s_nop 11
	global_load_dwordx4 v[144:147], v150, s[10:11]
	s_sub_u32 s34, s34, 196608
	s_subb_u32 s35, s35, 0
	s_sub_u32 s10, s10, 196608
	s_subb_u32 s11, s11, 0
	v_permlane32_swap_b32_e32 v16, v48
	v_permlane32_swap_b32_e32 v17, v49
	v_permlane32_swap_b32_e32 v18, v50
	v_permlane32_swap_b32_e32 v19, v51
	v_permlane32_swap_b32_e32 v20, v52
	v_permlane32_swap_b32_e32 v21, v53
	v_permlane32_swap_b32_e32 v22, v54
	v_permlane32_swap_b32_e32 v23, v55
	v_permlane32_swap_b32_e32 v24, v56
	v_permlane32_swap_b32_e32 v25, v57
	v_permlane32_swap_b32_e32 v26, v58
	v_permlane32_swap_b32_e32 v27, v59
	v_permlane32_swap_b32_e32 v28, v60
	v_permlane32_swap_b32_e32 v29, v61
	v_permlane32_swap_b32_e32 v30, v62
	v_permlane32_swap_b32_e32 v31, v63
	v_permlane32_swap_b32_e32 v32, v64
	v_permlane32_swap_b32_e32 v33, v65
	v_permlane32_swap_b32_e32 v34, v66
	v_permlane32_swap_b32_e32 v35, v67
	v_permlane32_swap_b32_e32 v36, v68
	v_permlane32_swap_b32_e32 v37, v69
	v_permlane32_swap_b32_e32 v38, v70
	v_permlane32_swap_b32_e32 v39, v71
	v_permlane32_swap_b32_e32 v40, v72
	v_permlane32_swap_b32_e32 v41, v73
	v_permlane32_swap_b32_e32 v42, v74
	v_permlane32_swap_b32_e32 v43, v75
	v_permlane32_swap_b32_e32 v44, v76
	v_permlane32_swap_b32_e32 v45, v77
	v_permlane32_swap_b32_e32 v46, v78
	v_permlane32_swap_b32_e32 v47, v79
	v_fmac_f32_e32 v63, v116, v120
	v_fmac_f32_e32 v79, v118, v121
	v_fmac_f32_dpp v63, v120, v122 quad_perm:[1,0,3,2] row_mask:0xf bank_mask:0xf
	v_fmac_f32_dpp v79, v121, v123 quad_perm:[1,0,3,2] row_mask:0xf bank_mask:0xf
	v_cvt_pk_bf16_f32 v148, v63, v79
	ds_write_b32 v151, v148 offset:8432
	v_fmac_f32_e32 v62, v116, v63
	v_fmac_f32_e32 v78, v118, v79
	v_fmac_f32_dpp v62, v63, v122 quad_perm:[1,0,3,2] row_mask:0xf bank_mask:0xf
	v_fmac_f32_dpp v78, v79, v123 quad_perm:[1,0,3,2] row_mask:0xf bank_mask:0xf
	v_cvt_pk_bf16_f32 v149, v62, v78
	ds_write_b32 v151, v149 offset:8160
	v_fmac_f32_e32 v61, v116, v62
	v_fmac_f32_e32 v77, v118, v78
	v_fmac_f32_dpp v61, v62, v122 quad_perm:[1,0,3,2] row_mask:0xf bank_mask:0xf
	v_fmac_f32_dpp v77, v78, v123 quad_perm:[1,0,3,2] row_mask:0xf bank_mask:0xf
	v_cvt_pk_bf16_f32 v148, v61, v77
	ds_write_b32 v151, v148 offset:7888
	v_fmac_f32_e32 v60, v116, v61
	v_fmac_f32_e32 v76, v118, v77
	v_fmac_f32_dpp v60, v61, v122 quad_perm:[1,0,3,2] row_mask:0xf bank_mask:0xf
	v_fmac_f32_dpp v76, v77, v123 quad_perm:[1,0,3,2] row_mask:0xf bank_mask:0xf
	v_cvt_pk_bf16_f32 v149, v60, v76
	ds_write_b32 v151, v149 offset:7616
	v_fmac_f32_e32 v31, v116, v60
	v_fmac_f32_e32 v47, v118, v76
	v_fmac_f32_dpp v31, v60, v122 quad_perm:[1,0,3,2] row_mask:0xf bank_mask:0xf
	v_fmac_f32_dpp v47, v76, v123 quad_perm:[1,0,3,2] row_mask:0xf bank_mask:0xf
	v_cvt_pk_bf16_f32 v148, v31, v47
	ds_write_b32 v151, v148 offset:7344
	v_fmac_f32_e32 v30, v116, v31
	v_fmac_f32_e32 v46, v118, v47
	v_fmac_f32_dpp v30, v31, v122 quad_perm:[1,0,3,2] row_mask:0xf bank_mask:0xf
	v_fmac_f32_dpp v46, v47, v123 quad_perm:[1,0,3,2] row_mask:0xf bank_mask:0xf
	v_cvt_pk_bf16_f32 v149, v30, v46
	ds_write_b32 v151, v149 offset:7072
	v_fmac_f32_e32 v29, v116, v30
	v_fmac_f32_e32 v45, v118, v46
	v_fmac_f32_dpp v29, v30, v122 quad_perm:[1,0,3,2] row_mask:0xf bank_mask:0xf
	v_fmac_f32_dpp v45, v46, v123 quad_perm:[1,0,3,2] row_mask:0xf bank_mask:0xf
	v_cvt_pk_bf16_f32 v148, v29, v45
	ds_write_b32 v151, v148 offset:6800
	v_fmac_f32_e32 v28, v116, v29
	v_fmac_f32_e32 v44, v118, v45
	v_fmac_f32_dpp v28, v29, v122 quad_perm:[1,0,3,2] row_mask:0xf bank_mask:0xf
	v_fmac_f32_dpp v44, v45, v123 quad_perm:[1,0,3,2] row_mask:0xf bank_mask:0xf
	v_cvt_pk_bf16_f32 v149, v28, v44
	ds_write_b32 v151, v149 offset:6528
	v_fmac_f32_e32 v59, v116, v28
	v_fmac_f32_e32 v75, v118, v44
	v_fmac_f32_dpp v59, v28, v122 quad_perm:[1,0,3,2] row_mask:0xf bank_mask:0xf
	v_fmac_f32_dpp v75, v44, v123 quad_perm:[1,0,3,2] row_mask:0xf bank_mask:0xf
	v_cvt_pk_bf16_f32 v148, v59, v75
	ds_write_b32 v151, v148 offset:6256
	v_fmac_f32_e32 v58, v116, v59
	v_fmac_f32_e32 v74, v118, v75
	v_fmac_f32_dpp v58, v59, v122 quad_perm:[1,0,3,2] row_mask:0xf bank_mask:0xf
	v_fmac_f32_dpp v74, v75, v123 quad_perm:[1,0,3,2] row_mask:0xf bank_mask:0xf
	v_cvt_pk_bf16_f32 v149, v58, v74
	ds_write_b32 v151, v149 offset:5984
	v_fmac_f32_e32 v57, v116, v58
	v_fmac_f32_e32 v73, v118, v74
	v_fmac_f32_dpp v57, v58, v122 quad_perm:[1,0,3,2] row_mask:0xf bank_mask:0xf
	v_fmac_f32_dpp v73, v74, v123 quad_perm:[1,0,3,2] row_mask:0xf bank_mask:0xf
	v_cvt_pk_bf16_f32 v148, v57, v73
	ds_write_b32 v151, v148 offset:5712
	v_fmac_f32_e32 v56, v116, v57
	v_fmac_f32_e32 v72, v118, v73
	v_fmac_f32_dpp v56, v57, v122 quad_perm:[1,0,3,2] row_mask:0xf bank_mask:0xf
	v_fmac_f32_dpp v72, v73, v123 quad_perm:[1,0,3,2] row_mask:0xf bank_mask:0xf
	v_cvt_pk_bf16_f32 v149, v56, v72
	ds_write_b32 v151, v149 offset:5440
	v_fmac_f32_e32 v27, v116, v56
	v_fmac_f32_e32 v43, v118, v72
	v_fmac_f32_dpp v27, v56, v122 quad_perm:[1,0,3,2] row_mask:0xf bank_mask:0xf
	v_fmac_f32_dpp v43, v72, v123 quad_perm:[1,0,3,2] row_mask:0xf bank_mask:0xf
	v_cvt_pk_bf16_f32 v148, v27, v43
	ds_write_b32 v151, v148 offset:5168
	v_fmac_f32_e32 v26, v116, v27
	v_fmac_f32_e32 v42, v118, v43
	v_fmac_f32_dpp v26, v27, v122 quad_perm:[1,0,3,2] row_mask:0xf bank_mask:0xf
	v_fmac_f32_dpp v42, v43, v123 quad_perm:[1,0,3,2] row_mask:0xf bank_mask:0xf
	v_cvt_pk_bf16_f32 v149, v26, v42
	ds_write_b32 v151, v149 offset:4896
	v_fmac_f32_e32 v25, v116, v26
	v_fmac_f32_e32 v41, v118, v42
	v_fmac_f32_dpp v25, v26, v122 quad_perm:[1,0,3,2] row_mask:0xf bank_mask:0xf
	v_fmac_f32_dpp v41, v42, v123 quad_perm:[1,0,3,2] row_mask:0xf bank_mask:0xf
	v_cvt_pk_bf16_f32 v148, v25, v41
	ds_write_b32 v151, v148 offset:4624
	v_fmac_f32_e32 v24, v116, v25
	v_fmac_f32_e32 v40, v118, v41
	v_fmac_f32_dpp v24, v25, v122 quad_perm:[1,0,3,2] row_mask:0xf bank_mask:0xf
	v_fmac_f32_dpp v40, v41, v123 quad_perm:[1,0,3,2] row_mask:0xf bank_mask:0xf
	v_cvt_pk_bf16_f32 v149, v24, v40
	ds_write_b32 v151, v149 offset:4352
	v_fmac_f32_e32 v55, v116, v24
	v_fmac_f32_e32 v71, v118, v40
	v_fmac_f32_dpp v55, v24, v122 quad_perm:[1,0,3,2] row_mask:0xf bank_mask:0xf
	v_fmac_f32_dpp v71, v40, v123 quad_perm:[1,0,3,2] row_mask:0xf bank_mask:0xf
	v_cvt_pk_bf16_f32 v148, v55, v71
	ds_write_b32 v151, v148 offset:4080
	v_fmac_f32_e32 v54, v116, v55
	v_fmac_f32_e32 v70, v118, v71
	v_fmac_f32_dpp v54, v55, v122 quad_perm:[1,0,3,2] row_mask:0xf bank_mask:0xf
	v_fmac_f32_dpp v70, v71, v123 quad_perm:[1,0,3,2] row_mask:0xf bank_mask:0xf
	v_cvt_pk_bf16_f32 v149, v54, v70
	ds_write_b32 v151, v149 offset:3808
	v_fmac_f32_e32 v53, v116, v54
	v_fmac_f32_e32 v69, v118, v70
	v_fmac_f32_dpp v53, v54, v122 quad_perm:[1,0,3,2] row_mask:0xf bank_mask:0xf
	v_fmac_f32_dpp v69, v70, v123 quad_perm:[1,0,3,2] row_mask:0xf bank_mask:0xf
	v_cvt_pk_bf16_f32 v148, v53, v69
	ds_write_b32 v151, v148 offset:3536
	v_fmac_f32_e32 v52, v116, v53
	v_fmac_f32_e32 v68, v118, v69
	v_fmac_f32_dpp v52, v53, v122 quad_perm:[1,0,3,2] row_mask:0xf bank_mask:0xf
	v_fmac_f32_dpp v68, v69, v123 quad_perm:[1,0,3,2] row_mask:0xf bank_mask:0xf
	v_cvt_pk_bf16_f32 v149, v52, v68
	ds_write_b32 v151, v149 offset:3264
	v_fmac_f32_e32 v23, v116, v52
	v_fmac_f32_e32 v39, v118, v68
	v_fmac_f32_dpp v23, v52, v122 quad_perm:[1,0,3,2] row_mask:0xf bank_mask:0xf
	v_fmac_f32_dpp v39, v68, v123 quad_perm:[1,0,3,2] row_mask:0xf bank_mask:0xf
	v_cvt_pk_bf16_f32 v148, v23, v39
	ds_write_b32 v151, v148 offset:2992
	v_fmac_f32_e32 v22, v116, v23
	v_fmac_f32_e32 v38, v118, v39
	v_fmac_f32_dpp v22, v23, v122 quad_perm:[1,0,3,2] row_mask:0xf bank_mask:0xf
	v_fmac_f32_dpp v38, v39, v123 quad_perm:[1,0,3,2] row_mask:0xf bank_mask:0xf
	v_cvt_pk_bf16_f32 v149, v22, v38
	ds_write_b32 v151, v149 offset:2720
	v_fmac_f32_e32 v21, v116, v22
	v_fmac_f32_e32 v37, v118, v38
	v_fmac_f32_dpp v21, v22, v122 quad_perm:[1,0,3,2] row_mask:0xf bank_mask:0xf
	v_fmac_f32_dpp v37, v38, v123 quad_perm:[1,0,3,2] row_mask:0xf bank_mask:0xf
	v_cvt_pk_bf16_f32 v148, v21, v37
	ds_write_b32 v151, v148 offset:2448
	v_fmac_f32_e32 v20, v116, v21
	v_fmac_f32_e32 v36, v118, v37
	v_fmac_f32_dpp v20, v21, v122 quad_perm:[1,0,3,2] row_mask:0xf bank_mask:0xf
	v_fmac_f32_dpp v36, v37, v123 quad_perm:[1,0,3,2] row_mask:0xf bank_mask:0xf
	v_cvt_pk_bf16_f32 v149, v20, v36
	ds_write_b32 v151, v149 offset:2176
	v_fmac_f32_e32 v51, v116, v20
	v_fmac_f32_e32 v67, v118, v36
	v_fmac_f32_dpp v51, v20, v122 quad_perm:[1,0,3,2] row_mask:0xf bank_mask:0xf
	v_fmac_f32_dpp v67, v36, v123 quad_perm:[1,0,3,2] row_mask:0xf bank_mask:0xf
	v_cvt_pk_bf16_f32 v148, v51, v67
	ds_write_b32 v151, v148 offset:1904
	v_fmac_f32_e32 v50, v116, v51
	v_fmac_f32_e32 v66, v118, v67
	v_fmac_f32_dpp v50, v51, v122 quad_perm:[1,0,3,2] row_mask:0xf bank_mask:0xf
	v_fmac_f32_dpp v66, v67, v123 quad_perm:[1,0,3,2] row_mask:0xf bank_mask:0xf
	v_cvt_pk_bf16_f32 v149, v50, v66
	ds_write_b32 v151, v149 offset:1632
	v_fmac_f32_e32 v49, v116, v50
	v_fmac_f32_e32 v65, v118, v66
	v_fmac_f32_dpp v49, v50, v122 quad_perm:[1,0,3,2] row_mask:0xf bank_mask:0xf
	v_fmac_f32_dpp v65, v66, v123 quad_perm:[1,0,3,2] row_mask:0xf bank_mask:0xf
	v_cvt_pk_bf16_f32 v148, v49, v65
	ds_write_b32 v151, v148 offset:1360
	v_fmac_f32_e32 v48, v116, v49
	v_fmac_f32_e32 v64, v118, v65
	v_fmac_f32_dpp v48, v49, v122 quad_perm:[1,0,3,2] row_mask:0xf bank_mask:0xf
	v_fmac_f32_dpp v64, v65, v123 quad_perm:[1,0,3,2] row_mask:0xf bank_mask:0xf
	v_cvt_pk_bf16_f32 v149, v48, v64
	ds_write_b32 v151, v149 offset:1088
	v_fmac_f32_e32 v19, v116, v48
	v_fmac_f32_e32 v35, v118, v64
	v_fmac_f32_dpp v19, v48, v122 quad_perm:[1,0,3,2] row_mask:0xf bank_mask:0xf
	v_fmac_f32_dpp v35, v64, v123 quad_perm:[1,0,3,2] row_mask:0xf bank_mask:0xf
	v_cvt_pk_bf16_f32 v148, v19, v35
	ds_write_b32 v151, v148 offset:816
	v_fmac_f32_e32 v18, v116, v19
	v_fmac_f32_e32 v34, v118, v35
	v_fmac_f32_dpp v18, v19, v122 quad_perm:[1,0,3,2] row_mask:0xf bank_mask:0xf
	v_fmac_f32_dpp v34, v35, v123 quad_perm:[1,0,3,2] row_mask:0xf bank_mask:0xf
	v_cvt_pk_bf16_f32 v149, v18, v34
	ds_write_b32 v151, v149 offset:544
	v_fmac_f32_e32 v17, v116, v18
	v_fmac_f32_e32 v33, v118, v34
	v_fmac_f32_dpp v17, v18, v122 quad_perm:[1,0,3,2] row_mask:0xf bank_mask:0xf
	v_fmac_f32_dpp v33, v34, v123 quad_perm:[1,0,3,2] row_mask:0xf bank_mask:0xf
	v_cvt_pk_bf16_f32 v148, v17, v33
	ds_write_b32 v151, v148 offset:272
	v_fmac_f32_e32 v16, v116, v17
	v_fmac_f32_e32 v32, v118, v33
	v_fmac_f32_dpp v16, v17, v122 quad_perm:[1,0,3,2] row_mask:0xf bank_mask:0xf
	v_fmac_f32_dpp v32, v33, v123 quad_perm:[1,0,3,2] row_mask:0xf bank_mask:0xf
	v_cvt_pk_bf16_f32 v149, v16, v32
	ds_write_b32 v151, v149
	v_mov_b32_e32 v120, v16
	v_mov_b32_e32 v121, v32
	ds_read_b128 v[124:127], v152
	ds_read_b128 v[128:131], v152 offset:64
	ds_read_b128 v[132:135], v152 offset:128
	ds_read_b128 v[136:139], v152 offset:192
	s_waitcnt lgkmcnt(3)
	v_mfma_f32_16x16x32_bf16 v[140:143], v[100:103], v[124:127], 0
	s_waitcnt lgkmcnt(2)
	v_mfma_f32_16x16x32_bf16 v[140:143], v[104:107], v[128:131], v[140:143]
	s_waitcnt lgkmcnt(1)
	v_mfma_f32_16x16x32_bf16 v[140:143], v[108:111], v[132:135], v[140:143]
	s_waitcnt lgkmcnt(0)
	v_mfma_f32_16x16x32_bf16 v[140:143], v[112:115], v[136:139], v[140:143]
	s_nop 9
	global_store_dwordx4 v153, v[140:143], s[12:13]
	s_nop 1
	ds_read_b128 v[124:127], v152 offset:4352
	ds_read_b128 v[128:131], v152 offset:4416
	ds_read_b128 v[132:135], v152 offset:4480
	ds_read_b128 v[136:139], v152 offset:4544
	s_waitcnt lgkmcnt(3)
	v_mfma_f32_16x16x32_bf16 v[140:143], v[100:103], v[124:127], 0
	s_waitcnt lgkmcnt(2)
	v_mfma_f32_16x16x32_bf16 v[140:143], v[104:107], v[128:131], v[140:143]
	s_waitcnt lgkmcnt(1)
	v_mfma_f32_16x16x32_bf16 v[140:143], v[108:111], v[132:135], v[140:143]
	s_waitcnt lgkmcnt(0)
	v_mfma_f32_16x16x32_bf16 v[140:143], v[112:115], v[136:139], v[140:143]
	s_nop 9
	global_store_dwordx4 v157, v[140:143], s[12:13]
	s_nop 1
	s_sub_u32 s12, s12, 2048
	s_subb_u32 s13, s13, 0
	s_add_u32 s14, s14, 2
	s_cmp_lt_u32 s14, 16
	s_cbranch_scc1 .Lssm_tileA_d1m0
	s_waitcnt vmcnt(0) lgkmcnt(0)
	s_lshr_b32 s21, s89, 1
	s_lshl_b32 s21, s21, 2
	s_add_u32 s37, s21, 0x21000
	v_mov_b32_e32 v182, s37
	v_mov_b32_e32 v183, 1
	v_cmp_eq_u32_e32 vcc, 0, v191
	s_and_saveexec_b64 s[0:1], vcc
	ds_add_u32 v182, v183
	s_mov_b64 exec, s[0:1]
	s_waitcnt lgkmcnt(0)
	s_mov_b32 s38, 0

.Lssm_spin_done_d1m0:
	s_mov_b64 s[42:43], s[6:7]
	s_sub_u32 s42, s42, 2048
	s_subb_u32 s43, s43, 0
	s_lshl_b32 s31, s25, 11
	s_lshl_b32 s29, s24, 5
	s_add_u32 s31, s31, s29
	s_add_u32 s31, s31, 344915968
	s_add_u32 s12, s62, s31
	s_addc_u32 s13, s63, 0
	s_mov_b64 s[64:65], s[34:35]
	s_add_u32 s64, s64, 196608
	s_addc_u32 s65, s65, 0
	global_load_dwordx4 v[6:9], v153, s[42:43]
	global_load_dwordx4 v[10:13], v157, s[42:43]
	s_sub_u32 s42, s42, 2048
	s_subb_u32 s43, s43, 0
	s_waitcnt vmcnt(0)
.Lssm_tileB_d1m0:
	s_waitcnt vmcnt(7)
	v_mfma_f32_32x32x16_bf16 v[16:31], v[80:83], v[84:87], 0
	v_mfma_f32_32x32x16_bf16 v[32:47], v[80:83], v[88:91], 0
	v_mfma_f32_32x32x16_bf16 v[48:63], v[80:83], v[92:95], 0
	v_mfma_f32_32x32x16_bf16 v[64:79], v[80:83], v[96:99], 0
	ds_write_b128 v162, v[80:83]
	global_load_dwordx4 v[172:175], v153, s[42:43]
	global_load_dwordx4 v[176:179], v157, s[42:43]
	s_sub_u32 s42, s42, 2048
	s_subb_u32 s43, s43, 0
	s_nop 11
	global_load_dwordx4 v[80:83], v150, s[10:11]
	s_sub_u32 s34, s34, 196608
	s_subb_u32 s35, s35, 0
	s_sub_u32 s10, s10, 196608
	s_subb_u32 s11, s11, 0
	v_permlane32_swap_b32_e32 v16, v48
	v_permlane32_swap_b32_e32 v17, v49
	v_permlane32_swap_b32_e32 v18, v50
	v_permlane32_swap_b32_e32 v19, v51
	v_permlane32_swap_b32_e32 v20, v52
	v_permlane32_swap_b32_e32 v21, v53
	v_permlane32_swap_b32_e32 v22, v54
	v_permlane32_swap_b32_e32 v23, v55
	v_permlane32_swap_b32_e32 v24, v56
	v_permlane32_swap_b32_e32 v25, v57
	v_permlane32_swap_b32_e32 v26, v58
	v_permlane32_swap_b32_e32 v27, v59
	v_permlane32_swap_b32_e32 v28, v60
	v_permlane32_swap_b32_e32 v29, v61
	v_permlane32_swap_b32_e32 v30, v62
	v_permlane32_swap_b32_e32 v31, v63
	v_permlane32_swap_b32_e32 v32, v64
	v_permlane32_swap_b32_e32 v33, v65
	v_permlane32_swap_b32_e32 v34, v66
	v_permlane32_swap_b32_e32 v35, v67
	v_permlane32_swap_b32_e32 v36, v68
	v_permlane32_swap_b32_e32 v37, v69
	v_permlane32_swap_b32_e32 v38, v70
	v_permlane32_swap_b32_e32 v39, v71
	v_permlane32_swap_b32_e32 v40, v72
	v_permlane32_swap_b32_e32 v41, v73
	v_permlane32_swap_b32_e32 v42, v74
	v_permlane32_swap_b32_e32 v43, v75
	v_permlane32_swap_b32_e32 v44, v76
	v_permlane32_swap_b32_e32 v45, v77
	v_permlane32_swap_b32_e32 v46, v78
	v_permlane32_swap_b32_e32 v47, v79
	v_fmac_f32_e32 v63, v116, v120
	v_fmac_f32_e32 v79, v118, v121
	v_fmac_f32_dpp v63, v120, v122 quad_perm:[1,0,3,2] row_mask:0xf bank_mask:0xf
	v_fmac_f32_dpp v79, v121, v123 quad_perm:[1,0,3,2] row_mask:0xf bank_mask:0xf
	v_cvt_pk_bf16_f32 v148, v63, v79
	ds_write_b32 v151, v148 offset:8432
	v_fmac_f32_e32 v62, v116, v63
	v_fmac_f32_e32 v78, v118, v79
	v_fmac_f32_dpp v62, v63, v122 quad_perm:[1,0,3,2] row_mask:0xf bank_mask:0xf
	v_fmac_f32_dpp v78, v79, v123 quad_perm:[1,0,3,2] row_mask:0xf bank_mask:0xf
	v_cvt_pk_bf16_f32 v149, v62, v78
	ds_write_b32 v151, v149 offset:8160
	v_fmac_f32_e32 v61, v116, v62
	v_fmac_f32_e32 v77, v118, v78
	v_fmac_f32_dpp v61, v62, v122 quad_perm:[1,0,3,2] row_mask:0xf bank_mask:0xf
	v_fmac_f32_dpp v77, v78, v123 quad_perm:[1,0,3,2] row_mask:0xf bank_mask:0xf
	v_cvt_pk_bf16_f32 v148, v61, v77
	ds_write_b32 v151, v148 offset:7888
	v_fmac_f32_e32 v60, v116, v61
	v_fmac_f32_e32 v76, v118, v77
	v_fmac_f32_dpp v60, v61, v122 quad_perm:[1,0,3,2] row_mask:0xf bank_mask:0xf
	v_fmac_f32_dpp v76, v77, v123 quad_perm:[1,0,3,2] row_mask:0xf bank_mask:0xf
	v_cvt_pk_bf16_f32 v149, v60, v76
	ds_write_b32 v151, v149 offset:7616
	v_fmac_f32_e32 v31, v116, v60
	v_fmac_f32_e32 v47, v118, v76
	v_fmac_f32_dpp v31, v60, v122 quad_perm:[1,0,3,2] row_mask:0xf bank_mask:0xf
	v_fmac_f32_dpp v47, v76, v123 quad_perm:[1,0,3,2] row_mask:0xf bank_mask:0xf
	v_cvt_pk_bf16_f32 v148, v31, v47
	ds_write_b32 v151, v148 offset:7344
	v_fmac_f32_e32 v30, v116, v31
	v_fmac_f32_e32 v46, v118, v47
	v_fmac_f32_dpp v30, v31, v122 quad_perm:[1,0,3,2] row_mask:0xf bank_mask:0xf
	v_fmac_f32_dpp v46, v47, v123 quad_perm:[1,0,3,2] row_mask:0xf bank_mask:0xf
	v_cvt_pk_bf16_f32 v149, v30, v46
	ds_write_b32 v151, v149 offset:7072
	v_fmac_f32_e32 v29, v116, v30
	v_fmac_f32_e32 v45, v118, v46
	v_fmac_f32_dpp v29, v30, v122 quad_perm:[1,0,3,2] row_mask:0xf bank_mask:0xf
	v_fmac_f32_dpp v45, v46, v123 quad_perm:[1,0,3,2] row_mask:0xf bank_mask:0xf
	v_cvt_pk_bf16_f32 v148, v29, v45
	ds_write_b32 v151, v148 offset:6800
	v_fmac_f32_e32 v28, v116, v29
	v_fmac_f32_e32 v44, v118, v45
	v_fmac_f32_dpp v28, v29, v122 quad_perm:[1,0,3,2] row_mask:0xf bank_mask:0xf
	v_fmac_f32_dpp v44, v45, v123 quad_perm:[1,0,3,2] row_mask:0xf bank_mask:0xf
	v_cvt_pk_bf16_f32 v149, v28, v44
	ds_write_b32 v151, v149 offset:6528
	v_fmac_f32_e32 v59, v116, v28
	v_fmac_f32_e32 v75, v118, v44
	v_fmac_f32_dpp v59, v28, v122 quad_perm:[1,0,3,2] row_mask:0xf bank_mask:0xf
	v_fmac_f32_dpp v75, v44, v123 quad_perm:[1,0,3,2] row_mask:0xf bank_mask:0xf
	v_cvt_pk_bf16_f32 v148, v59, v75
	ds_write_b32 v151, v148 offset:6256
	v_fmac_f32_e32 v58, v116, v59
	v_fmac_f32_e32 v74, v118, v75
	v_fmac_f32_dpp v58, v59, v122 quad_perm:[1,0,3,2] row_mask:0xf bank_mask:0xf
	v_fmac_f32_dpp v74, v75, v123 quad_perm:[1,0,3,2] row_mask:0xf bank_mask:0xf
	v_cvt_pk_bf16_f32 v149, v58, v74
	ds_write_b32 v151, v149 offset:5984
	v_fmac_f32_e32 v57, v116, v58
	v_fmac_f32_e32 v73, v118, v74
	v_fmac_f32_dpp v57, v58, v122 quad_perm:[1,0,3,2] row_mask:0xf bank_mask:0xf
	v_fmac_f32_dpp v73, v74, v123 quad_perm:[1,0,3,2] row_mask:0xf bank_mask:0xf
	v_cvt_pk_bf16_f32 v148, v57, v73
	ds_write_b32 v151, v148 offset:5712
	v_fmac_f32_e32 v56, v116, v57
	v_fmac_f32_e32 v72, v118, v73
	v_fmac_f32_dpp v56, v57, v122 quad_perm:[1,0,3,2] row_mask:0xf bank_mask:0xf
	v_fmac_f32_dpp v72, v73, v123 quad_perm:[1,0,3,2] row_mask:0xf bank_mask:0xf
	v_cvt_pk_bf16_f32 v149, v56, v72
	ds_write_b32 v151, v149 offset:5440
	v_fmac_f32_e32 v27, v116, v56
	v_fmac_f32_e32 v43, v118, v72
	v_fmac_f32_dpp v27, v56, v122 quad_perm:[1,0,3,2] row_mask:0xf bank_mask:0xf
	v_fmac_f32_dpp v43, v72, v123 quad_perm:[1,0,3,2] row_mask:0xf bank_mask:0xf
	v_cvt_pk_bf16_f32 v148, v27, v43
	ds_write_b32 v151, v148 offset:5168
	v_fmac_f32_e32 v26, v116, v27
	v_fmac_f32_e32 v42, v118, v43
	v_fmac_f32_dpp v26, v27, v122 quad_perm:[1,0,3,2] row_mask:0xf bank_mask:0xf
	v_fmac_f32_dpp v42, v43, v123 quad_perm:[1,0,3,2] row_mask:0xf bank_mask:0xf
	v_cvt_pk_bf16_f32 v149, v26, v42
	ds_write_b32 v151, v149 offset:4896
	v_fmac_f32_e32 v25, v116, v26
	v_fmac_f32_e32 v41, v118, v42
	v_fmac_f32_dpp v25, v26, v122 quad_perm:[1,0,3,2] row_mask:0xf bank_mask:0xf
	v_fmac_f32_dpp v41, v42, v123 quad_perm:[1,0,3,2] row_mask:0xf bank_mask:0xf
	v_cvt_pk_bf16_f32 v148, v25, v41
	ds_write_b32 v151, v148 offset:4624
	v_fmac_f32_e32 v24, v116, v25
	v_fmac_f32_e32 v40, v118, v41
	v_fmac_f32_dpp v24, v25, v122 quad_perm:[1,0,3,2] row_mask:0xf bank_mask:0xf
	v_fmac_f32_dpp v40, v41, v123 quad_perm:[1,0,3,2] row_mask:0xf bank_mask:0xf
	v_cvt_pk_bf16_f32 v149, v24, v40
	ds_write_b32 v151, v149 offset:4352
	v_fmac_f32_e32 v55, v116, v24
	v_fmac_f32_e32 v71, v118, v40
	v_fmac_f32_dpp v55, v24, v122 quad_perm:[1,0,3,2] row_mask:0xf bank_mask:0xf
	v_fmac_f32_dpp v71, v40, v123 quad_perm:[1,0,3,2] row_mask:0xf bank_mask:0xf
	v_cvt_pk_bf16_f32 v148, v55, v71
	ds_write_b32 v151, v148 offset:4080
	v_fmac_f32_e32 v54, v116, v55
	v_fmac_f32_e32 v70, v118, v71
	v_fmac_f32_dpp v54, v55, v122 quad_perm:[1,0,3,2] row_mask:0xf bank_mask:0xf
	v_fmac_f32_dpp v70, v71, v123 quad_perm:[1,0,3,2] row_mask:0xf bank_mask:0xf
	v_cvt_pk_bf16_f32 v149, v54, v70
	ds_write_b32 v151, v149 offset:3808
	v_fmac_f32_e32 v53, v116, v54
	v_fmac_f32_e32 v69, v118, v70
	v_fmac_f32_dpp v53, v54, v122 quad_perm:[1,0,3,2] row_mask:0xf bank_mask:0xf
	v_fmac_f32_dpp v69, v70, v123 quad_perm:[1,0,3,2] row_mask:0xf bank_mask:0xf
	v_cvt_pk_bf16_f32 v148, v53, v69
	ds_write_b32 v151, v148 offset:3536
	v_fmac_f32_e32 v52, v116, v53
	v_fmac_f32_e32 v68, v118, v69
	v_fmac_f32_dpp v52, v53, v122 quad_perm:[1,0,3,2] row_mask:0xf bank_mask:0xf
	v_fmac_f32_dpp v68, v69, v123 quad_perm:[1,0,3,2] row_mask:0xf bank_mask:0xf
	v_cvt_pk_bf16_f32 v149, v52, v68
	ds_write_b32 v151, v149 offset:3264
	v_fmac_f32_e32 v23, v116, v52
	v_fmac_f32_e32 v39, v118, v68
	v_fmac_f32_dpp v23, v52, v122 quad_perm:[1,0,3,2] row_mask:0xf bank_mask:0xf
	v_fmac_f32_dpp v39, v68, v123 quad_perm:[1,0,3,2] row_mask:0xf bank_mask:0xf
	v_cvt_pk_bf16_f32 v148, v23, v39
	ds_write_b32 v151, v148 offset:2992
	v_fmac_f32_e32 v22, v116, v23
	v_fmac_f32_e32 v38, v118, v39
	v_fmac_f32_dpp v22, v23, v122 quad_perm:[1,0,3,2] row_mask:0xf bank_mask:0xf
	v_fmac_f32_dpp v38, v39, v123 quad_perm:[1,0,3,2] row_mask:0xf bank_mask:0xf
	v_cvt_pk_bf16_f32 v149, v22, v38
	ds_write_b32 v151, v149 offset:2720
	v_fmac_f32_e32 v21, v116, v22
	v_fmac_f32_e32 v37, v118, v38
	v_fmac_f32_dpp v21, v22, v122 quad_perm:[1,0,3,2] row_mask:0xf bank_mask:0xf
	v_fmac_f32_dpp v37, v38, v123 quad_perm:[1,0,3,2] row_mask:0xf bank_mask:0xf
	v_cvt_pk_bf16_f32 v148, v21, v37
	ds_write_b32 v151, v148 offset:2448
	v_fmac_f32_e32 v20, v116, v21
	v_fmac_f32_e32 v36, v118, v37
	v_fmac_f32_dpp v20, v21, v122 quad_perm:[1,0,3,2] row_mask:0xf bank_mask:0xf
	v_fmac_f32_dpp v36, v37, v123 quad_perm:[1,0,3,2] row_mask:0xf bank_mask:0xf
	v_cvt_pk_bf16_f32 v149, v20, v36
	ds_write_b32 v151, v149 offset:2176
	v_fmac_f32_e32 v51, v116, v20
	v_fmac_f32_e32 v67, v118, v36
	v_fmac_f32_dpp v51, v20, v122 quad_perm:[1,0,3,2] row_mask:0xf bank_mask:0xf
	v_fmac_f32_dpp v67, v36, v123 quad_perm:[1,0,3,2] row_mask:0xf bank_mask:0xf
	v_cvt_pk_bf16_f32 v148, v51, v67
	ds_write_b32 v151, v148 offset:1904
	v_fmac_f32_e32 v50, v116, v51
	v_fmac_f32_e32 v66, v118, v67
	v_fmac_f32_dpp v50, v51, v122 quad_perm:[1,0,3,2] row_mask:0xf bank_mask:0xf
	v_fmac_f32_dpp v66, v67, v123 quad_perm:[1,0,3,2] row_mask:0xf bank_mask:0xf
	v_cvt_pk_bf16_f32 v149, v50, v66
	ds_write_b32 v151, v149 offset:1632
	v_fmac_f32_e32 v49, v116, v50
	v_fmac_f32_e32 v65, v118, v66
	v_fmac_f32_dpp v49, v50, v122 quad_perm:[1,0,3,2] row_mask:0xf bank_mask:0xf
	v_fmac_f32_dpp v65, v66, v123 quad_perm:[1,0,3,2] row_mask:0xf bank_mask:0xf
	v_cvt_pk_bf16_f32 v148, v49, v65
	ds_write_b32 v151, v148 offset:1360
	v_fmac_f32_e32 v48, v116, v49
	v_fmac_f32_e32 v64, v118, v65
	v_fmac_f32_dpp v48, v49, v122 quad_perm:[1,0,3,2] row_mask:0xf bank_mask:0xf
	v_fmac_f32_dpp v64, v65, v123 quad_perm:[1,0,3,2] row_mask:0xf bank_mask:0xf
	v_cvt_pk_bf16_f32 v149, v48, v64
	ds_write_b32 v151, v149 offset:1088
	v_fmac_f32_e32 v19, v116, v48
	v_fmac_f32_e32 v35, v118, v64
	v_fmac_f32_dpp v19, v48, v122 quad_perm:[1,0,3,2] row_mask:0xf bank_mask:0xf
	v_fmac_f32_dpp v35, v64, v123 quad_perm:[1,0,3,2] row_mask:0xf bank_mask:0xf
	v_cvt_pk_bf16_f32 v148, v19, v35
	ds_write_b32 v151, v148 offset:816
	v_fmac_f32_e32 v18, v116, v19
	v_fmac_f32_e32 v34, v118, v35
	v_fmac_f32_dpp v18, v19, v122 quad_perm:[1,0,3,2] row_mask:0xf bank_mask:0xf
	v_fmac_f32_dpp v34, v35, v123 quad_perm:[1,0,3,2] row_mask:0xf bank_mask:0xf
	v_cvt_pk_bf16_f32 v149, v18, v34
	ds_write_b32 v151, v149 offset:544
	v_fmac_f32_e32 v17, v116, v18
	v_fmac_f32_e32 v33, v118, v34
	v_fmac_f32_dpp v17, v18, v122 quad_perm:[1,0,3,2] row_mask:0xf bank_mask:0xf
	v_fmac_f32_dpp v33, v34, v123 quad_perm:[1,0,3,2] row_mask:0xf bank_mask:0xf
	v_cvt_pk_bf16_f32 v148, v17, v33
	ds_write_b32 v151, v148 offset:272
	v_fmac_f32_e32 v16, v116, v17
	v_fmac_f32_e32 v32, v118, v33
	v_fmac_f32_dpp v16, v17, v122 quad_perm:[1,0,3,2] row_mask:0xf bank_mask:0xf
	v_fmac_f32_dpp v32, v33, v123 quad_perm:[1,0,3,2] row_mask:0xf bank_mask:0xf
	v_cvt_pk_bf16_f32 v149, v16, v32
	ds_write_b32 v151, v149
	v_mov_b32_e32 v120, v16
	v_mov_b32_e32 v121, v32
	ds_read_b128 v[124:127], v152
	ds_read_b128 v[128:131], v152 offset:64
	ds_read_b128 v[132:135], v152 offset:128
	ds_read_b128 v[136:139], v152 offset:192
	ds_read_b64 v[160:161], v163
	s_waitcnt lgkmcnt(4)
	v_mfma_f32_16x16x32_bf16 v[140:143], v[100:103], v[124:127], 0
	s_waitcnt lgkmcnt(3)
	v_mfma_f32_16x16x32_bf16 v[140:143], v[104:107], v[128:131], v[140:143]
	s_waitcnt lgkmcnt(2)
	v_mfma_f32_16x16x32_bf16 v[140:143], v[108:111], v[132:135], v[140:143]
	s_waitcnt lgkmcnt(1)
	v_mfma_f32_16x16x32_bf16 v[140:143], v[112:115], v[136:139], v[140:143]
	s_nop 9
	s_waitcnt vmcnt(7) lgkmcnt(0)
	v_add_f32_e32 v182, v6, v140
	v_add_f32_e32 v183, v7, v141
	v_add_f32_e32 v184, v8, v142
	v_add_f32_e32 v185, v9, v143
	v_lshlrev_b32_e32 v186, 16, v160
	v_and_b32_e32 v187, 0xffff0000, v160
	v_lshlrev_b32_e32 v188, 16, v161
	v_and_b32_e32 v189, 0xffff0000, v161
	v_fmac_f32_e32 v182, v164, v186
	v_fmac_f32_e32 v183, v165, v187
	v_fmac_f32_e32 v184, v166, v188
	v_fmac_f32_e32 v185, v167, v189
	v_mul_f32_e32 v186, 0x3d372713, v182
	v_mul_f32_e32 v187, 0x3d372713, v183
	v_mul_f32_e32 v188, 0x3d372713, v184
	v_mul_f32_e32 v189, 0x3d372713, v185
	v_mul_f32_e32 v186, v182, v186
	v_mul_f32_e32 v187, v183, v187
	v_mul_f32_e32 v188, v184, v188
	v_mul_f32_e32 v189, v185, v189
	v_fma_f32 v186, v182, v186, v182
	v_fma_f32 v187, v183, v187, v183
	v_fma_f32 v188, v184, v188, v184
	v_fma_f32 v189, v185, v189, v185
	v_mul_f32_e32 v186, 0xbfcc422a, v186
	v_mul_f32_e32 v187, 0xbfcc422a, v187
	v_mul_f32_e32 v188, 0xbfcc422a, v188
	v_mul_f32_e32 v189, 0xbfcc422a, v189
	v_mul_f32_e32 v186, 0x3fb8aa3b, v186
	v_mul_f32_e32 v187, 0x3fb8aa3b, v187
	v_mul_f32_e32 v188, 0x3fb8aa3b, v188
	v_mul_f32_e32 v189, 0x3fb8aa3b, v189
	v_exp_f32_e32 v186, v186
	v_exp_f32_e32 v187, v187
	v_exp_f32_e32 v188, v188
	v_exp_f32_e32 v189, v189
	v_add_f32_e32 v186, 1.0, v186
	v_add_f32_e32 v187, 1.0, v187
	v_add_f32_e32 v188, 1.0, v188
	v_add_f32_e32 v189, 1.0, v189
	v_rcp_f32_e32 v186, v186
	v_rcp_f32_e32 v187, v187
	v_rcp_f32_e32 v188, v188
	v_rcp_f32_e32 v189, v189
	v_mul_f32_e32 v182, v182, v186
	v_mul_f32_e32 v183, v183, v187
	v_mul_f32_e32 v184, v184, v188
	v_mul_f32_e32 v185, v185, v189
	v_cvt_pk_bf16_f32 v148, v182, v183
	v_cvt_pk_bf16_f32 v149, v184, v185
	global_store_dwordx2 v156, v[148:149], s[12:13]
	ds_read_b128 v[124:127], v152 offset:4352
	ds_read_b128 v[128:131], v152 offset:4416
	ds_read_b128 v[132:135], v152 offset:4480
	ds_read_b128 v[136:139], v152 offset:4544
	ds_read_b64 v[160:161], v163 offset:512
	s_waitcnt lgkmcnt(4)
	v_mfma_f32_16x16x32_bf16 v[140:143], v[100:103], v[124:127], 0
	s_waitcnt lgkmcnt(3)
	v_mfma_f32_16x16x32_bf16 v[140:143], v[104:107], v[128:131], v[140:143]
	s_waitcnt lgkmcnt(2)
	v_mfma_f32_16x16x32_bf16 v[140:143], v[108:111], v[132:135], v[140:143]
	s_waitcnt lgkmcnt(1)
	v_mfma_f32_16x16x32_bf16 v[140:143], v[112:115], v[136:139], v[140:143]
	s_nop 9
	s_waitcnt vmcnt(7) lgkmcnt(0)
	v_add_f32_e32 v182, v10, v140
	v_add_f32_e32 v183, v11, v141
	v_add_f32_e32 v184, v12, v142
	v_add_f32_e32 v185, v13, v143
	v_lshlrev_b32_e32 v186, 16, v160
	v_and_b32_e32 v187, 0xffff0000, v160
	v_lshlrev_b32_e32 v188, 16, v161
	v_and_b32_e32 v189, 0xffff0000, v161
	v_fmac_f32_e32 v182, v164, v186
	v_fmac_f32_e32 v183, v165, v187
	v_fmac_f32_e32 v184, v166, v188
	v_fmac_f32_e32 v185, v167, v189
	v_mul_f32_e32 v186, 0x3d372713, v182
	v_mul_f32_e32 v187, 0x3d372713, v183
	v_mul_f32_e32 v188, 0x3d372713, v184
	v_mul_f32_e32 v189, 0x3d372713, v185
	v_mul_f32_e32 v186, v182, v186
	v_mul_f32_e32 v187, v183, v187
	v_mul_f32_e32 v188, v184, v188
	v_mul_f32_e32 v189, v185, v189
	v_fma_f32 v186, v182, v186, v182
	v_fma_f32 v187, v183, v187, v183
	v_fma_f32 v188, v184, v188, v184
	v_fma_f32 v189, v185, v189, v185
	v_mul_f32_e32 v186, 0xbfcc422a, v186
	v_mul_f32_e32 v187, 0xbfcc422a, v187
	v_mul_f32_e32 v188, 0xbfcc422a, v188
	v_mul_f32_e32 v189, 0xbfcc422a, v189
	v_mul_f32_e32 v186, 0x3fb8aa3b, v186
	v_mul_f32_e32 v187, 0x3fb8aa3b, v187
	v_mul_f32_e32 v188, 0x3fb8aa3b, v188
	v_mul_f32_e32 v189, 0x3fb8aa3b, v189
	v_exp_f32_e32 v186, v186
	v_exp_f32_e32 v187, v187
	v_exp_f32_e32 v188, v188
	v_exp_f32_e32 v189, v189
	v_add_f32_e32 v186, 1.0, v186
	v_add_f32_e32 v187, 1.0, v187
	v_add_f32_e32 v188, 1.0, v188
	v_add_f32_e32 v189, 1.0, v189
	v_rcp_f32_e32 v186, v186
	v_rcp_f32_e32 v187, v187
	v_rcp_f32_e32 v188, v188
	v_rcp_f32_e32 v189, v189
	v_mul_f32_e32 v182, v182, v186
	v_mul_f32_e32 v183, v183, v187
	v_mul_f32_e32 v184, v184, v188
	v_mul_f32_e32 v185, v185, v189
	v_cvt_pk_bf16_f32 v148, v182, v183
	v_cvt_pk_bf16_f32 v149, v184, v185
	global_store_dwordx2 v159, v[148:149], s[12:13]
	s_sub_u32 s12, s12, 65536
	s_subb_u32 s13, s13, 0
	s_waitcnt vmcnt(7)
	v_mfma_f32_32x32x16_bf16 v[16:31], v[144:147], v[84:87], 0
	v_mfma_f32_32x32x16_bf16 v[32:47], v[144:147], v[88:91], 0
	v_mfma_f32_32x32x16_bf16 v[48:63], v[144:147], v[92:95], 0
	v_mfma_f32_32x32x16_bf16 v[64:79], v[144:147], v[96:99], 0
	ds_write_b128 v162, v[144:147]
	global_load_dwordx4 v[6:9], v153, s[42:43]
	global_load_dwordx4 v[10:13], v157, s[42:43]
	s_sub_u32 s42, s42, 2048
	s_subb_u32 s43, s43, 0
	s_nop 11
	global_load_dwordx4 v[144:147], v150, s[10:11]
	s_sub_u32 s34, s34, 196608
	s_subb_u32 s35, s35, 0
	s_sub_u32 s10, s10, 196608
	s_subb_u32 s11, s11, 0
	v_permlane32_swap_b32_e32 v16, v48
	v_permlane32_swap_b32_e32 v17, v49
	v_permlane32_swap_b32_e32 v18, v50
	v_permlane32_swap_b32_e32 v19, v51
	v_permlane32_swap_b32_e32 v20, v52
	v_permlane32_swap_b32_e32 v21, v53
	v_permlane32_swap_b32_e32 v22, v54
	v_permlane32_swap_b32_e32 v23, v55
	v_permlane32_swap_b32_e32 v24, v56
	v_permlane32_swap_b32_e32 v25, v57
	v_permlane32_swap_b32_e32 v26, v58
	v_permlane32_swap_b32_e32 v27, v59
	v_permlane32_swap_b32_e32 v28, v60
	v_permlane32_swap_b32_e32 v29, v61
	v_permlane32_swap_b32_e32 v30, v62
	v_permlane32_swap_b32_e32 v31, v63
	v_permlane32_swap_b32_e32 v32, v64
	v_permlane32_swap_b32_e32 v33, v65
	v_permlane32_swap_b32_e32 v34, v66
	v_permlane32_swap_b32_e32 v35, v67
	v_permlane32_swap_b32_e32 v36, v68
	v_permlane32_swap_b32_e32 v37, v69
	v_permlane32_swap_b32_e32 v38, v70
	v_permlane32_swap_b32_e32 v39, v71
	v_permlane32_swap_b32_e32 v40, v72
	v_permlane32_swap_b32_e32 v41, v73
	v_permlane32_swap_b32_e32 v42, v74
	v_permlane32_swap_b32_e32 v43, v75
	v_permlane32_swap_b32_e32 v44, v76
	v_permlane32_swap_b32_e32 v45, v77
	v_permlane32_swap_b32_e32 v46, v78
	v_permlane32_swap_b32_e32 v47, v79
	v_fmac_f32_e32 v63, v116, v120
	v_fmac_f32_e32 v79, v118, v121
	v_fmac_f32_dpp v63, v120, v122 quad_perm:[1,0,3,2] row_mask:0xf bank_mask:0xf
	v_fmac_f32_dpp v79, v121, v123 quad_perm:[1,0,3,2] row_mask:0xf bank_mask:0xf
	v_cvt_pk_bf16_f32 v148, v63, v79
	ds_write_b32 v151, v148 offset:8432
	v_fmac_f32_e32 v62, v116, v63
	v_fmac_f32_e32 v78, v118, v79
	v_fmac_f32_dpp v62, v63, v122 quad_perm:[1,0,3,2] row_mask:0xf bank_mask:0xf
	v_fmac_f32_dpp v78, v79, v123 quad_perm:[1,0,3,2] row_mask:0xf bank_mask:0xf
	v_cvt_pk_bf16_f32 v149, v62, v78
	ds_write_b32 v151, v149 offset:8160
	v_fmac_f32_e32 v61, v116, v62
	v_fmac_f32_e32 v77, v118, v78
	v_fmac_f32_dpp v61, v62, v122 quad_perm:[1,0,3,2] row_mask:0xf bank_mask:0xf
	v_fmac_f32_dpp v77, v78, v123 quad_perm:[1,0,3,2] row_mask:0xf bank_mask:0xf
	v_cvt_pk_bf16_f32 v148, v61, v77
	ds_write_b32 v151, v148 offset:7888
	v_fmac_f32_e32 v60, v116, v61
	v_fmac_f32_e32 v76, v118, v77
	v_fmac_f32_dpp v60, v61, v122 quad_perm:[1,0,3,2] row_mask:0xf bank_mask:0xf
	v_fmac_f32_dpp v76, v77, v123 quad_perm:[1,0,3,2] row_mask:0xf bank_mask:0xf
	v_cvt_pk_bf16_f32 v149, v60, v76
	ds_write_b32 v151, v149 offset:7616
	v_fmac_f32_e32 v31, v116, v60
	v_fmac_f32_e32 v47, v118, v76
	v_fmac_f32_dpp v31, v60, v122 quad_perm:[1,0,3,2] row_mask:0xf bank_mask:0xf
	v_fmac_f32_dpp v47, v76, v123 quad_perm:[1,0,3,2] row_mask:0xf bank_mask:0xf
	v_cvt_pk_bf16_f32 v148, v31, v47
	ds_write_b32 v151, v148 offset:7344
	v_fmac_f32_e32 v30, v116, v31
	v_fmac_f32_e32 v46, v118, v47
	v_fmac_f32_dpp v30, v31, v122 quad_perm:[1,0,3,2] row_mask:0xf bank_mask:0xf
	v_fmac_f32_dpp v46, v47, v123 quad_perm:[1,0,3,2] row_mask:0xf bank_mask:0xf
	v_cvt_pk_bf16_f32 v149, v30, v46
	ds_write_b32 v151, v149 offset:7072
	v_fmac_f32_e32 v29, v116, v30
	v_fmac_f32_e32 v45, v118, v46
	v_fmac_f32_dpp v29, v30, v122 quad_perm:[1,0,3,2] row_mask:0xf bank_mask:0xf
	v_fmac_f32_dpp v45, v46, v123 quad_perm:[1,0,3,2] row_mask:0xf bank_mask:0xf
	v_cvt_pk_bf16_f32 v148, v29, v45
	ds_write_b32 v151, v148 offset:6800
	v_fmac_f32_e32 v28, v116, v29
	v_fmac_f32_e32 v44, v118, v45
	v_fmac_f32_dpp v28, v29, v122 quad_perm:[1,0,3,2] row_mask:0xf bank_mask:0xf
	v_fmac_f32_dpp v44, v45, v123 quad_perm:[1,0,3,2] row_mask:0xf bank_mask:0xf
	v_cvt_pk_bf16_f32 v149, v28, v44
	ds_write_b32 v151, v149 offset:6528
	v_fmac_f32_e32 v59, v116, v28
	v_fmac_f32_e32 v75, v118, v44
	v_fmac_f32_dpp v59, v28, v122 quad_perm:[1,0,3,2] row_mask:0xf bank_mask:0xf
	v_fmac_f32_dpp v75, v44, v123 quad_perm:[1,0,3,2] row_mask:0xf bank_mask:0xf
	v_cvt_pk_bf16_f32 v148, v59, v75
	ds_write_b32 v151, v148 offset:6256
	v_fmac_f32_e32 v58, v116, v59
	v_fmac_f32_e32 v74, v118, v75
	v_fmac_f32_dpp v58, v59, v122 quad_perm:[1,0,3,2] row_mask:0xf bank_mask:0xf
	v_fmac_f32_dpp v74, v75, v123 quad_perm:[1,0,3,2] row_mask:0xf bank_mask:0xf
	v_cvt_pk_bf16_f32 v149, v58, v74
	ds_write_b32 v151, v149 offset:5984
	v_fmac_f32_e32 v57, v116, v58
	v_fmac_f32_e32 v73, v118, v74
	v_fmac_f32_dpp v57, v58, v122 quad_perm:[1,0,3,2] row_mask:0xf bank_mask:0xf
	v_fmac_f32_dpp v73, v74, v123 quad_perm:[1,0,3,2] row_mask:0xf bank_mask:0xf
	v_cvt_pk_bf16_f32 v148, v57, v73
	ds_write_b32 v151, v148 offset:5712
	v_fmac_f32_e32 v56, v116, v57
	v_fmac_f32_e32 v72, v118, v73
	v_fmac_f32_dpp v56, v57, v122 quad_perm:[1,0,3,2] row_mask:0xf bank_mask:0xf
	v_fmac_f32_dpp v72, v73, v123 quad_perm:[1,0,3,2] row_mask:0xf bank_mask:0xf
	v_cvt_pk_bf16_f32 v149, v56, v72
	ds_write_b32 v151, v149 offset:5440
	v_fmac_f32_e32 v27, v116, v56
	v_fmac_f32_e32 v43, v118, v72
	v_fmac_f32_dpp v27, v56, v122 quad_perm:[1,0,3,2] row_mask:0xf bank_mask:0xf
	v_fmac_f32_dpp v43, v72, v123 quad_perm:[1,0,3,2] row_mask:0xf bank_mask:0xf
	v_cvt_pk_bf16_f32 v148, v27, v43
	ds_write_b32 v151, v148 offset:5168
	v_fmac_f32_e32 v26, v116, v27
	v_fmac_f32_e32 v42, v118, v43
	v_fmac_f32_dpp v26, v27, v122 quad_perm:[1,0,3,2] row_mask:0xf bank_mask:0xf
	v_fmac_f32_dpp v42, v43, v123 quad_perm:[1,0,3,2] row_mask:0xf bank_mask:0xf
	v_cvt_pk_bf16_f32 v149, v26, v42
	ds_write_b32 v151, v149 offset:4896
	v_fmac_f32_e32 v25, v116, v26
	v_fmac_f32_e32 v41, v118, v42
	v_fmac_f32_dpp v25, v26, v122 quad_perm:[1,0,3,2] row_mask:0xf bank_mask:0xf
	v_fmac_f32_dpp v41, v42, v123 quad_perm:[1,0,3,2] row_mask:0xf bank_mask:0xf
	v_cvt_pk_bf16_f32 v148, v25, v41
	ds_write_b32 v151, v148 offset:4624
	v_fmac_f32_e32 v24, v116, v25
	v_fmac_f32_e32 v40, v118, v41
	v_fmac_f32_dpp v24, v25, v122 quad_perm:[1,0,3,2] row_mask:0xf bank_mask:0xf
	v_fmac_f32_dpp v40, v41, v123 quad_perm:[1,0,3,2] row_mask:0xf bank_mask:0xf
	v_cvt_pk_bf16_f32 v149, v24, v40
	ds_write_b32 v151, v149 offset:4352
	v_fmac_f32_e32 v55, v116, v24
	v_fmac_f32_e32 v71, v118, v40
	v_fmac_f32_dpp v55, v24, v122 quad_perm:[1,0,3,2] row_mask:0xf bank_mask:0xf
	v_fmac_f32_dpp v71, v40, v123 quad_perm:[1,0,3,2] row_mask:0xf bank_mask:0xf
	v_cvt_pk_bf16_f32 v148, v55, v71
	ds_write_b32 v151, v148 offset:4080
	v_fmac_f32_e32 v54, v116, v55
	v_fmac_f32_e32 v70, v118, v71
	v_fmac_f32_dpp v54, v55, v122 quad_perm:[1,0,3,2] row_mask:0xf bank_mask:0xf
	v_fmac_f32_dpp v70, v71, v123 quad_perm:[1,0,3,2] row_mask:0xf bank_mask:0xf
	v_cvt_pk_bf16_f32 v149, v54, v70
	ds_write_b32 v151, v149 offset:3808
	v_fmac_f32_e32 v53, v116, v54
	v_fmac_f32_e32 v69, v118, v70
	v_fmac_f32_dpp v53, v54, v122 quad_perm:[1,0,3,2] row_mask:0xf bank_mask:0xf
	v_fmac_f32_dpp v69, v70, v123 quad_perm:[1,0,3,2] row_mask:0xf bank_mask:0xf
	v_cvt_pk_bf16_f32 v148, v53, v69
	ds_write_b32 v151, v148 offset:3536
	v_fmac_f32_e32 v52, v116, v53
	v_fmac_f32_e32 v68, v118, v69
	v_fmac_f32_dpp v52, v53, v122 quad_perm:[1,0,3,2] row_mask:0xf bank_mask:0xf
	v_fmac_f32_dpp v68, v69, v123 quad_perm:[1,0,3,2] row_mask:0xf bank_mask:0xf
	v_cvt_pk_bf16_f32 v149, v52, v68
	ds_write_b32 v151, v149 offset:3264
	v_fmac_f32_e32 v23, v116, v52
	v_fmac_f32_e32 v39, v118, v68
	v_fmac_f32_dpp v23, v52, v122 quad_perm:[1,0,3,2] row_mask:0xf bank_mask:0xf
	v_fmac_f32_dpp v39, v68, v123 quad_perm:[1,0,3,2] row_mask:0xf bank_mask:0xf
	v_cvt_pk_bf16_f32 v148, v23, v39
	ds_write_b32 v151, v148 offset:2992
	v_fmac_f32_e32 v22, v116, v23
	v_fmac_f32_e32 v38, v118, v39
	v_fmac_f32_dpp v22, v23, v122 quad_perm:[1,0,3,2] row_mask:0xf bank_mask:0xf
	v_fmac_f32_dpp v38, v39, v123 quad_perm:[1,0,3,2] row_mask:0xf bank_mask:0xf
	v_cvt_pk_bf16_f32 v149, v22, v38
	ds_write_b32 v151, v149 offset:2720
	v_fmac_f32_e32 v21, v116, v22
	v_fmac_f32_e32 v37, v118, v38
	v_fmac_f32_dpp v21, v22, v122 quad_perm:[1,0,3,2] row_mask:0xf bank_mask:0xf
	v_fmac_f32_dpp v37, v38, v123 quad_perm:[1,0,3,2] row_mask:0xf bank_mask:0xf
	v_cvt_pk_bf16_f32 v148, v21, v37
	ds_write_b32 v151, v148 offset:2448
	v_fmac_f32_e32 v20, v116, v21
	v_fmac_f32_e32 v36, v118, v37
	v_fmac_f32_dpp v20, v21, v122 quad_perm:[1,0,3,2] row_mask:0xf bank_mask:0xf
	v_fmac_f32_dpp v36, v37, v123 quad_perm:[1,0,3,2] row_mask:0xf bank_mask:0xf
	v_cvt_pk_bf16_f32 v149, v20, v36
	ds_write_b32 v151, v149 offset:2176
	v_fmac_f32_e32 v51, v116, v20
	v_fmac_f32_e32 v67, v118, v36
	v_fmac_f32_dpp v51, v20, v122 quad_perm:[1,0,3,2] row_mask:0xf bank_mask:0xf
	v_fmac_f32_dpp v67, v36, v123 quad_perm:[1,0,3,2] row_mask:0xf bank_mask:0xf
	v_cvt_pk_bf16_f32 v148, v51, v67
	ds_write_b32 v151, v148 offset:1904
	v_fmac_f32_e32 v50, v116, v51
	v_fmac_f32_e32 v66, v118, v67
	v_fmac_f32_dpp v50, v51, v122 quad_perm:[1,0,3,2] row_mask:0xf bank_mask:0xf
	v_fmac_f32_dpp v66, v67, v123 quad_perm:[1,0,3,2] row_mask:0xf bank_mask:0xf
	v_cvt_pk_bf16_f32 v149, v50, v66
	ds_write_b32 v151, v149 offset:1632
	v_fmac_f32_e32 v49, v116, v50
	v_fmac_f32_e32 v65, v118, v66
	v_fmac_f32_dpp v49, v50, v122 quad_perm:[1,0,3,2] row_mask:0xf bank_mask:0xf
	v_fmac_f32_dpp v65, v66, v123 quad_perm:[1,0,3,2] row_mask:0xf bank_mask:0xf
	v_cvt_pk_bf16_f32 v148, v49, v65
	ds_write_b32 v151, v148 offset:1360
	v_fmac_f32_e32 v48, v116, v49
	v_fmac_f32_e32 v64, v118, v65
	v_fmac_f32_dpp v48, v49, v122 quad_perm:[1,0,3,2] row_mask:0xf bank_mask:0xf
	v_fmac_f32_dpp v64, v65, v123 quad_perm:[1,0,3,2] row_mask:0xf bank_mask:0xf
	v_cvt_pk_bf16_f32 v149, v48, v64
	ds_write_b32 v151, v149 offset:1088
	v_fmac_f32_e32 v19, v116, v48
	v_fmac_f32_e32 v35, v118, v64
	v_fmac_f32_dpp v19, v48, v122 quad_perm:[1,0,3,2] row_mask:0xf bank_mask:0xf
	v_fmac_f32_dpp v35, v64, v123 quad_perm:[1,0,3,2] row_mask:0xf bank_mask:0xf
	v_cvt_pk_bf16_f32 v148, v19, v35
	ds_write_b32 v151, v148 offset:816
	v_fmac_f32_e32 v18, v116, v19
	v_fmac_f32_e32 v34, v118, v35
	v_fmac_f32_dpp v18, v19, v122 quad_perm:[1,0,3,2] row_mask:0xf bank_mask:0xf
	v_fmac_f32_dpp v34, v35, v123 quad_perm:[1,0,3,2] row_mask:0xf bank_mask:0xf
	v_cvt_pk_bf16_f32 v149, v18, v34
	ds_write_b32 v151, v149 offset:544
	v_fmac_f32_e32 v17, v116, v18
	v_fmac_f32_e32 v33, v118, v34
	v_fmac_f32_dpp v17, v18, v122 quad_perm:[1,0,3,2] row_mask:0xf bank_mask:0xf
	v_fmac_f32_dpp v33, v34, v123 quad_perm:[1,0,3,2] row_mask:0xf bank_mask:0xf
	v_cvt_pk_bf16_f32 v148, v17, v33
	ds_write_b32 v151, v148 offset:272
	v_fmac_f32_e32 v16, v116, v17
	v_fmac_f32_e32 v32, v118, v33
	v_fmac_f32_dpp v16, v17, v122 quad_perm:[1,0,3,2] row_mask:0xf bank_mask:0xf
	v_fmac_f32_dpp v32, v33, v123 quad_perm:[1,0,3,2] row_mask:0xf bank_mask:0xf
	v_cvt_pk_bf16_f32 v149, v16, v32
	ds_write_b32 v151, v149
	v_mov_b32_e32 v120, v16
	v_mov_b32_e32 v121, v32
	ds_read_b128 v[124:127], v152
	ds_read_b128 v[128:131], v152 offset:64
	ds_read_b128 v[132:135], v152 offset:128
	ds_read_b128 v[136:139], v152 offset:192
	ds_read_b64 v[160:161], v163
	s_waitcnt lgkmcnt(4)
	v_mfma_f32_16x16x32_bf16 v[140:143], v[100:103], v[124:127], 0
	s_waitcnt lgkmcnt(3)
	v_mfma_f32_16x16x32_bf16 v[140:143], v[104:107], v[128:131], v[140:143]
	s_waitcnt lgkmcnt(2)
	v_mfma_f32_16x16x32_bf16 v[140:143], v[108:111], v[132:135], v[140:143]
	s_waitcnt lgkmcnt(1)
	v_mfma_f32_16x16x32_bf16 v[140:143], v[112:115], v[136:139], v[140:143]
	s_nop 9
	s_waitcnt vmcnt(7) lgkmcnt(0)
	v_add_f32_e32 v182, v172, v140
	v_add_f32_e32 v183, v173, v141
	v_add_f32_e32 v184, v174, v142
	v_add_f32_e32 v185, v175, v143
	v_lshlrev_b32_e32 v186, 16, v160
	v_and_b32_e32 v187, 0xffff0000, v160
	v_lshlrev_b32_e32 v188, 16, v161
	v_and_b32_e32 v189, 0xffff0000, v161
	v_fmac_f32_e32 v182, v164, v186
	v_fmac_f32_e32 v183, v165, v187
	v_fmac_f32_e32 v184, v166, v188
	v_fmac_f32_e32 v185, v167, v189
	v_mul_f32_e32 v186, 0x3d372713, v182
	v_mul_f32_e32 v187, 0x3d372713, v183
	v_mul_f32_e32 v188, 0x3d372713, v184
	v_mul_f32_e32 v189, 0x3d372713, v185
	v_mul_f32_e32 v186, v182, v186
	v_mul_f32_e32 v187, v183, v187
	v_mul_f32_e32 v188, v184, v188
	v_mul_f32_e32 v189, v185, v189
	v_fma_f32 v186, v182, v186, v182
	v_fma_f32 v187, v183, v187, v183
	v_fma_f32 v188, v184, v188, v184
	v_fma_f32 v189, v185, v189, v185
	v_mul_f32_e32 v186, 0xbfcc422a, v186
	v_mul_f32_e32 v187, 0xbfcc422a, v187
	v_mul_f32_e32 v188, 0xbfcc422a, v188
	v_mul_f32_e32 v189, 0xbfcc422a, v189
	v_mul_f32_e32 v186, 0x3fb8aa3b, v186
	v_mul_f32_e32 v187, 0x3fb8aa3b, v187
	v_mul_f32_e32 v188, 0x3fb8aa3b, v188
	v_mul_f32_e32 v189, 0x3fb8aa3b, v189
	v_exp_f32_e32 v186, v186
	v_exp_f32_e32 v187, v187
	v_exp_f32_e32 v188, v188
	v_exp_f32_e32 v189, v189
	v_add_f32_e32 v186, 1.0, v186
	v_add_f32_e32 v187, 1.0, v187
	v_add_f32_e32 v188, 1.0, v188
	v_add_f32_e32 v189, 1.0, v189
	v_rcp_f32_e32 v186, v186
	v_rcp_f32_e32 v187, v187
	v_rcp_f32_e32 v188, v188
	v_rcp_f32_e32 v189, v189
	v_mul_f32_e32 v182, v182, v186
	v_mul_f32_e32 v183, v183, v187
	v_mul_f32_e32 v184, v184, v188
	v_mul_f32_e32 v185, v185, v189
	v_cvt_pk_bf16_f32 v148, v182, v183
	v_cvt_pk_bf16_f32 v149, v184, v185
	global_store_dwordx2 v156, v[148:149], s[12:13]
	ds_read_b128 v[124:127], v152 offset:4352
	ds_read_b128 v[128:131], v152 offset:4416
	ds_read_b128 v[132:135], v152 offset:4480
	ds_read_b128 v[136:139], v152 offset:4544
	ds_read_b64 v[160:161], v163 offset:512
	s_waitcnt lgkmcnt(4)
	v_mfma_f32_16x16x32_bf16 v[140:143], v[100:103], v[124:127], 0
	s_waitcnt lgkmcnt(3)
	v_mfma_f32_16x16x32_bf16 v[140:143], v[104:107], v[128:131], v[140:143]
	s_waitcnt lgkmcnt(2)
	v_mfma_f32_16x16x32_bf16 v[140:143], v[108:111], v[132:135], v[140:143]
	s_waitcnt lgkmcnt(1)
	v_mfma_f32_16x16x32_bf16 v[140:143], v[112:115], v[136:139], v[140:143]
	s_nop 9
	s_waitcnt vmcnt(7) lgkmcnt(0)
	v_add_f32_e32 v182, v176, v140
	v_add_f32_e32 v183, v177, v141
	v_add_f32_e32 v184, v178, v142
	v_add_f32_e32 v185, v179, v143
	v_lshlrev_b32_e32 v186, 16, v160
	v_and_b32_e32 v187, 0xffff0000, v160
	v_lshlrev_b32_e32 v188, 16, v161
	v_and_b32_e32 v189, 0xffff0000, v161
	v_fmac_f32_e32 v182, v164, v186
	v_fmac_f32_e32 v183, v165, v187
	v_fmac_f32_e32 v184, v166, v188
	v_fmac_f32_e32 v185, v167, v189
	v_mul_f32_e32 v186, 0x3d372713, v182
	v_mul_f32_e32 v187, 0x3d372713, v183
	v_mul_f32_e32 v188, 0x3d372713, v184
	v_mul_f32_e32 v189, 0x3d372713, v185
	v_mul_f32_e32 v186, v182, v186
	v_mul_f32_e32 v187, v183, v187
	v_mul_f32_e32 v188, v184, v188
	v_mul_f32_e32 v189, v185, v189
	v_fma_f32 v186, v182, v186, v182
	v_fma_f32 v187, v183, v187, v183
	v_fma_f32 v188, v184, v188, v184
	v_fma_f32 v189, v185, v189, v185
	v_mul_f32_e32 v186, 0xbfcc422a, v186
	v_mul_f32_e32 v187, 0xbfcc422a, v187
	v_mul_f32_e32 v188, 0xbfcc422a, v188
	v_mul_f32_e32 v189, 0xbfcc422a, v189
	v_mul_f32_e32 v186, 0x3fb8aa3b, v186
	v_mul_f32_e32 v187, 0x3fb8aa3b, v187
	v_mul_f32_e32 v188, 0x3fb8aa3b, v188
	v_mul_f32_e32 v189, 0x3fb8aa3b, v189
	v_exp_f32_e32 v186, v186
	v_exp_f32_e32 v187, v187
	v_exp_f32_e32 v188, v188
	v_exp_f32_e32 v189, v189
	v_add_f32_e32 v186, 1.0, v186
	v_add_f32_e32 v187, 1.0, v187
	v_add_f32_e32 v188, 1.0, v188
	v_add_f32_e32 v189, 1.0, v189
	v_rcp_f32_e32 v186, v186
	v_rcp_f32_e32 v187, v187
	v_rcp_f32_e32 v188, v188
	v_rcp_f32_e32 v189, v189
	v_mul_f32_e32 v182, v182, v186
	v_mul_f32_e32 v183, v183, v187
	v_mul_f32_e32 v184, v184, v188
	v_mul_f32_e32 v185, v185, v189
	v_cvt_pk_bf16_f32 v148, v182, v183
	v_cvt_pk_bf16_f32 v149, v184, v185
	global_store_dwordx2 v159, v[148:149], s[12:13]
	s_sub_u32 s12, s12, 65536
	s_subb_u32 s13, s13, 0
	s_add_u32 s14, s14, 2
	s_cmp_lt_u32 s14, 32
	s_cbranch_scc1 .Lssm_tileB_d1m0
	s_waitcnt vmcnt(0) lgkmcnt(0)
